# win/gemm_f32/ffn_up k-loops rotated: barrier after MFMA group 12, next iteration's first fragment reads fly during the last 3 groups (4 A buffers); ffn_up epilogue store addresses from immediates
# speedup vs baseline: 1.0097x; 1.0097x over previous
; template <int MI, int NJ> ...
;     ...
;   if (!pre) G8LOADP(Ag, Bg);
;   G8STORE(0);
;   {
;     const u16* ga_ = (1 < nk) ? Ag + 64 : Ag + nAoff;
;     const u16* gb_ = (1 < nk) ? Bg + 64 : Bg + nBoff;
;     G8LOADP(ga_, gb_);
;   }
;   __syncthreads();
;   const int sw0 = ((lane >> 4) ^ (lane & 7)) * 8;
;   const int dsw = (sw0 ^ 32) - sw0;
;   const u16* ra_ = sA + (wm * (16 * MI) + (lane & 15)) * 64 + sw0;
;   const u16* rb_ = sB + (wn * (16 * NJ) + (lane & 15)) * 64 + sw0;
;   for (int kt = 0; kt < nk; ++kt) {
;     const int buf = kt & 1;
;     {
;       G8STORE(buf ^ 1);
;       const u16* ga_ = (kt + 2 < nk) ? Ag + (kt + 2) * 64 : Ag + nAoff;
;       const u16* gb_ = (kt + 2 < nk) ? Bg + (kt + 2) * 64 : Bg + nBoff;
;       G8LOADP(ga_, gb_);
;     }
;     __builtin_amdgcn_sched_barrier(0);
;     __builtin_amdgcn_s_setprio(1);
;     const u16* a = ra_ + buf * AROWS * 64;
;     const u16* b = rb_ + buf * BROWS * 64;
.LBB0_469:
	s_waitcnt vmcnt(5)
	ds_write_b128 v185, v[10:13]
	ds_write_b128 v185, v[2:5] offset:8192
	ds_write_b128 v185, v[6:9] offset:16384
	s_waitcnt vmcnt(3)
	ds_write_b128 v185, v[18:21] offset:24576
	ds_write_b128 v186, v[14:17]
	s_waitcnt vmcnt(2)
	ds_write_b128 v186, v[22:25] offset:8192
	s_waitcnt vmcnt(1)
	ds_write_b128 v186, v[26:29] offset:16384
	s_waitcnt vmcnt(0)
	ds_write_b128 v186, v[30:33] offset:24576
	s_and_b32 s12, s39, 7
	s_sub_i32 s11, s12, s11
	s_lshl_b32 s12, s11, 8
	s_sub_i32 s11, s46, s37
	global_load_dwordx4 v[10:13], v234, s[62:63] offset:128
	global_load_dwordx4 v[2:5], v235, s[62:63] offset:128
	global_load_dwordx4 v[6:9], v236, s[62:63] offset:128
	global_load_dwordx4 v[18:21], v237, s[62:63] offset:128
	global_load_dwordx4 v[14:17], v234, s[64:65] offset:128
	global_load_dwordx4 v[22:25], v235, s[64:65] offset:128
	global_load_dwordx4 v[26:29], v236, s[64:65] offset:128
	global_load_dwordx4 v[30:33], v237, s[64:65] offset:128
	s_lshl_b32 s20, s11, 8
	s_ashr_i32 s13, s12, 31
	s_ashr_i32 s21, s20, 31
	v_mov_b32_e32 v34, 0
	s_lshl_b64 s[12:13], s[12:13], 10
	s_lshl_b64 s[46:47], s[20:21], 10
	s_mov_b32 s11, 0
	s_mov_b64 s[20:21], 0x80
	s_mov_b32 s37, 0
	v_mov_b32_e32 v35, v34
	v_mov_b32_e32 v36, v34
	v_mov_b32_e32 v37, v34
	v_mov_b32_e32 v38, v34
	v_mov_b32_e32 v39, v34
	v_mov_b32_e32 v40, v34
	v_mov_b32_e32 v41, v34
	v_mov_b32_e32 v42, v34
	v_mov_b32_e32 v43, v34
	v_mov_b32_e32 v44, v34
	v_mov_b32_e32 v45, v34
	v_mov_b32_e32 v46, v34
	v_mov_b32_e32 v47, v34
	v_mov_b32_e32 v48, v34
	v_mov_b32_e32 v49, v34
	v_mov_b32_e32 v50, v34
	v_mov_b32_e32 v51, v34
	v_mov_b32_e32 v52, v34
	v_mov_b32_e32 v53, v34
	v_mov_b32_e32 v54, v34
	v_mov_b32_e32 v55, v34
	v_mov_b32_e32 v56, v34
	v_mov_b32_e32 v57, v34
	v_mov_b32_e32 v58, v34
	v_mov_b32_e32 v59, v34
	v_mov_b32_e32 v60, v34
	v_mov_b32_e32 v61, v34
	v_mov_b32_e32 v62, v34
	v_mov_b32_e32 v63, v34
	v_mov_b32_e32 v64, v34
	v_mov_b32_e32 v65, v34
	v_mov_b32_e32 v66, v34
	v_mov_b32_e32 v67, v34
	v_mov_b32_e32 v68, v34
	v_mov_b32_e32 v69, v34
	v_mov_b32_e32 v70, v34
	v_mov_b32_e32 v71, v34
	v_mov_b32_e32 v72, v34
	v_mov_b32_e32 v73, v34
	v_mov_b32_e32 v74, v34
	v_mov_b32_e32 v75, v34
	v_mov_b32_e32 v76, v34
	v_mov_b32_e32 v77, v34
	v_mov_b32_e32 v78, v34
	v_mov_b32_e32 v79, v34
	v_mov_b32_e32 v80, v34
	v_mov_b32_e32 v81, v34
	v_mov_b32_e32 v82, v34
	v_mov_b32_e32 v83, v34
	v_mov_b32_e32 v84, v34
	v_mov_b32_e32 v85, v34
	v_mov_b32_e32 v86, v34
	v_mov_b32_e32 v87, v34
	v_mov_b32_e32 v88, v34
	v_mov_b32_e32 v89, v34
	v_mov_b32_e32 v90, v34
	v_mov_b32_e32 v91, v34
	v_mov_b32_e32 v92, v34
	v_mov_b32_e32 v93, v34
	v_mov_b32_e32 v94, v34
	v_mov_b32_e32 v95, v34
	v_mov_b32_e32 v96, v34
	v_mov_b32_e32 v97, v34
	v_mov_b32_e32 v98, v34
	v_mov_b32_e32 v99, v34
	v_mov_b32_e32 v100, v34
	v_mov_b32_e32 v101, v34
	v_mov_b32_e32 v102, v34
	v_mov_b32_e32 v103, v34
	v_mov_b32_e32 v104, v34
	v_mov_b32_e32 v105, v34
	v_mov_b32_e32 v106, v34
	v_mov_b32_e32 v107, v34
	v_mov_b32_e32 v108, v34
	v_mov_b32_e32 v109, v34
	v_mov_b32_e32 v110, v34
	v_mov_b32_e32 v111, v34
	v_mov_b32_e32 v112, v34
	v_mov_b32_e32 v113, v34
	v_mov_b32_e32 v114, v34
	v_mov_b32_e32 v115, v34
	v_mov_b32_e32 v116, v34
	v_mov_b32_e32 v117, v34
	v_mov_b32_e32 v118, v34
	v_mov_b32_e32 v119, v34
	v_mov_b32_e32 v120, v34
	v_mov_b32_e32 v121, v34
	v_mov_b32_e32 v122, v34
	v_mov_b32_e32 v123, v34
	v_mov_b32_e32 v124, v34
	v_mov_b32_e32 v125, v34
	v_mov_b32_e32 v126, v34
	v_mov_b32_e32 v127, v34
	v_mov_b32_e32 v128, v34
	v_mov_b32_e32 v129, v34
	v_mov_b32_e32 v130, v34
	v_mov_b32_e32 v131, v34
	v_mov_b32_e32 v132, v34
	v_mov_b32_e32 v133, v34
	v_mov_b32_e32 v134, v34
	v_mov_b32_e32 v135, v34
	v_mov_b32_e32 v136, v34
	v_mov_b32_e32 v137, v34
	v_mov_b32_e32 v138, v34
	v_mov_b32_e32 v139, v34
	v_mov_b32_e32 v140, v34
	v_mov_b32_e32 v141, v34
	v_mov_b32_e32 v142, v34
	v_mov_b32_e32 v143, v34
	v_mov_b32_e32 v144, v34
	v_mov_b32_e32 v145, v34
	v_mov_b32_e32 v146, v34
	v_mov_b32_e32 v147, v34
	v_mov_b32_e32 v148, v34
	v_mov_b32_e32 v149, v34
	v_mov_b32_e32 v150, v34
	v_mov_b32_e32 v151, v34
	v_mov_b32_e32 v152, v34
	v_mov_b32_e32 v153, v34
	v_mov_b32_e32 v154, v34
	v_mov_b32_e32 v155, v34
	v_mov_b32_e32 v156, v34
	v_mov_b32_e32 v157, v34
	v_mov_b32_e32 v158, v34
	v_mov_b32_e32 v159, v34
	v_mov_b32_e32 v160, v34
	v_mov_b32_e32 v161, v34
	s_waitcnt lgkmcnt(0)
	s_barrier
	s_and_b32 s38, s11, 0x4000
	s_xor_b32 s39, s38, 0x4000
	s_lshl_b32 s39, s39, 1
	v_add_u32_e32 v228, s39, v185
	v_add_u32_e32 v229, s39, v186
	s_cmp_lt_u32 s37, 14
	s_cselect_b32 s49, s21, s13
	s_cselect_b32 s48, s20, s12
	s_cselect_b32 s51, s21, s47
	s_cselect_b32 s50, s20, s46
	s_lshl_b64 s[48:49], s[48:49], 1
	s_lshl_b64 s[50:51], s[50:51], 1
	s_add_u32 s52, s62, s48
	s_addc_u32 s53, s63, s49
	s_add_u32 s66, s64, s50
	s_addc_u32 s67, s65, s51
	s_lshl_b32 s38, s38, 1
	v_add_u32_e32 v0, s38, v187
	v_add_u32_e32 v191, s38, v188
	ds_read_b128 v[166:169], v191
	ds_read_b128 v[162:165], v0
	ds_read_b128 v[170:173], v191 offset:2048
	ds_read_b128 v[192:195], v191 offset:4096
	ds_read_b128 v[196:199], v191 offset:6144
	ds_read_b128 v[204:207], v0 offset:2048
	ds_read_b128 v[208:211], v0 offset:4096
	ds_read_b128 v[238:241], v0 offset:6144
	v_add_u32_e32 v191, v191, v190
; template <int MI, int NJ> ...
;     ...
;   for (int kt = 0; kt < nk; ++kt) {
;     const int buf = kt & 1;
;     {
;       G8STORE(buf ^ 1);
;       const u16* ga_ = (kt + 2 < nk) ? Ag + (kt + 2) * 64 : Ag + nAoff;
;       const u16* gb_ = (kt + 2 < nk) ? Bg + (kt + 2) * 64 : Bg + nBoff;
;       G8LOADP(ga_, gb_);
;     }
;     __builtin_amdgcn_sched_barrier(0);
;     __builtin_amdgcn_s_setprio(1);
;     const u16* a = ra_ + buf * AROWS * 64;
;     const u16* b = rb_ + buf * BROWS * 64;
; #pragma unroll
;     for (int ks = 0; ks < 2; ++ks) {
;       const u16* a_ = ks ? a + dsw : a;
;       const u16* b_ = ks ? b + dsw : b;
;       bf16x8 bfr[NJ];
; #pragma unroll
;       for (int j = 0; j < NJ; ++j) bfr[j] = *(const bf16x8*)(b_ + j * 16 * 64);
; #pragma unroll
;       for (int ih = 0; ih < MI / 4; ++ih) {
;         bf16x8 af[4];
; #pragma unroll
;         for (int i = 0; i < 4; ++i) af[i] = *(const bf16x8*)(a_ + (ih * 4 + i) * 16 * 64);
; #pragma unroll
;         for (int i = 0; i < 4; ++i)
; #pragma unroll
;           for (int j = 0; j < NJ; ++j) acc[ih * 4 + i][j] = mfma16(af[i], bfr[j], acc[ih * 4 + i][j]);
;       }
;     }
;     __builtin_amdgcn_s_setprio(0);
;     __builtin_amdgcn_sched_barrier(0);
;     __syncthreads();
.LBB0_470:
	s_setprio 1
	s_waitcnt lgkmcnt(6)
	v_mfma_f32_16x16x32_bf16 v[158:161], v[166:169], v[162:165], v[158:161]
	s_waitcnt lgkmcnt(5)
	v_mfma_f32_16x16x32_bf16 v[154:157], v[170:173], v[162:165], v[154:157]
	s_waitcnt lgkmcnt(4)
	v_mfma_f32_16x16x32_bf16 v[150:153], v[192:195], v[162:165], v[150:153]
	s_waitcnt lgkmcnt(3)
	v_mfma_f32_16x16x32_bf16 v[146:149], v[196:199], v[162:165], v[146:149]
	ds_read_b128 v[162:165], v0 offset:8192
	s_waitcnt lgkmcnt(3)
	v_mfma_f32_16x16x32_bf16 v[142:145], v[166:169], v[204:207], v[142:145]
	v_mfma_f32_16x16x32_bf16 v[138:141], v[170:173], v[204:207], v[138:141]
	v_mfma_f32_16x16x32_bf16 v[134:137], v[192:195], v[204:207], v[134:137]
	v_mfma_f32_16x16x32_bf16 v[130:133], v[196:199], v[204:207], v[130:133]
	ds_read_b128 v[204:207], v0 offset:10240
	s_waitcnt vmcnt(7)
	ds_write_b128 v228, v[10:13]
	global_load_dwordx4 v[10:13], v234, s[52:53]
	s_waitcnt lgkmcnt(4)
	v_mfma_f32_16x16x32_bf16 v[126:129], v[166:169], v[208:211], v[126:129]
	v_mfma_f32_16x16x32_bf16 v[122:125], v[170:173], v[208:211], v[122:125]
	v_mfma_f32_16x16x32_bf16 v[118:121], v[192:195], v[208:211], v[118:121]
	v_mfma_f32_16x16x32_bf16 v[114:117], v[196:199], v[208:211], v[114:117]
	ds_read_b128 v[208:211], v0 offset:12288
	s_waitcnt vmcnt(7)
	ds_write_b128 v228, v[2:5] offset:8192
	global_load_dwordx4 v[2:5], v235, s[52:53]
	ds_read_b128 v[212:215], v191
	ds_read_b128 v[216:219], v191 offset:2048
	s_waitcnt lgkmcnt(7)
	v_mfma_f32_16x16x32_bf16 v[110:113], v[166:169], v[238:241], v[110:113]
	v_mfma_f32_16x16x32_bf16 v[106:109], v[170:173], v[238:241], v[106:109]
	v_mfma_f32_16x16x32_bf16 v[102:105], v[192:195], v[238:241], v[102:105]
	v_mfma_f32_16x16x32_bf16 v[98:101], v[196:199], v[238:241], v[98:101]
	ds_read_b128 v[238:241], v0 offset:14336
	s_waitcnt vmcnt(7)
	ds_write_b128 v228, v[6:9] offset:16384
	global_load_dwordx4 v[6:9], v236, s[52:53]
	ds_read_b128 v[220:223], v191 offset:4096
	ds_read_b128 v[224:227], v191 offset:6144
	s_waitcnt lgkmcnt(10)
	v_mfma_f32_16x16x32_bf16 v[94:97], v[166:169], v[162:165], v[94:97]
	v_mfma_f32_16x16x32_bf16 v[90:93], v[170:173], v[162:165], v[90:93]
	v_mfma_f32_16x16x32_bf16 v[86:89], v[192:195], v[162:165], v[86:89]
	v_mfma_f32_16x16x32_bf16 v[82:85], v[196:199], v[162:165], v[82:85]
	v_add_u32_e32 v0, v0, v190
	ds_read_b128 v[162:165], v0
	s_waitcnt vmcnt(7)
	ds_write_b128 v228, v[18:21] offset:24576
	global_load_dwordx4 v[18:21], v237, s[52:53]
	s_waitcnt lgkmcnt(11)
	v_mfma_f32_16x16x32_bf16 v[78:81], v[166:169], v[204:207], v[78:81]
	v_mfma_f32_16x16x32_bf16 v[74:77], v[170:173], v[204:207], v[74:77]
	v_mfma_f32_16x16x32_bf16 v[70:73], v[192:195], v[204:207], v[70:73]
	v_mfma_f32_16x16x32_bf16 v[66:69], v[196:199], v[204:207], v[66:69]
	ds_read_b128 v[204:207], v0 offset:2048
	s_waitcnt vmcnt(7)
	ds_write_b128 v229, v[14:17]
	global_load_dwordx4 v[14:17], v234, s[66:67]
	s_waitcnt lgkmcnt(11)
	v_mfma_f32_16x16x32_bf16 v[62:65], v[166:169], v[208:211], v[62:65]
	v_mfma_f32_16x16x32_bf16 v[58:61], v[170:173], v[208:211], v[58:61]
	v_mfma_f32_16x16x32_bf16 v[54:57], v[192:195], v[208:211], v[54:57]
	v_mfma_f32_16x16x32_bf16 v[50:53], v[196:199], v[208:211], v[50:53]
	ds_read_b128 v[208:211], v0 offset:4096
	s_waitcnt vmcnt(7)
	ds_write_b128 v229, v[22:25] offset:8192
	global_load_dwordx4 v[22:25], v235, s[66:67]
	s_waitcnt lgkmcnt(9)
	v_mfma_f32_16x16x32_bf16 v[46:49], v[166:169], v[238:241], v[46:49]
	v_mfma_f32_16x16x32_bf16 v[42:45], v[170:173], v[238:241], v[42:45]
	v_mfma_f32_16x16x32_bf16 v[38:41], v[192:195], v[238:241], v[38:41]
	v_mfma_f32_16x16x32_bf16 v[34:37], v[196:199], v[238:241], v[34:37]
	ds_read_b128 v[238:241], v0 offset:6144
	s_waitcnt vmcnt(7)
	ds_write_b128 v229, v[26:29] offset:16384
	global_load_dwordx4 v[26:29], v236, s[66:67]
	s_waitcnt lgkmcnt(7)
	v_mfma_f32_16x16x32_bf16 v[158:161], v[212:215], v[162:165], v[158:161]
	v_mfma_f32_16x16x32_bf16 v[154:157], v[216:219], v[162:165], v[154:157]
	v_mfma_f32_16x16x32_bf16 v[150:153], v[220:223], v[162:165], v[150:153]
	v_mfma_f32_16x16x32_bf16 v[146:149], v[224:227], v[162:165], v[146:149]
	ds_read_b128 v[162:165], v0 offset:8192
	s_waitcnt vmcnt(7)
	ds_write_b128 v229, v[30:33] offset:24576
	global_load_dwordx4 v[30:33], v237, s[66:67]
	s_waitcnt lgkmcnt(7)
	v_mfma_f32_16x16x32_bf16 v[142:145], v[212:215], v[204:207], v[142:145]
	v_mfma_f32_16x16x32_bf16 v[138:141], v[216:219], v[204:207], v[138:141]
	v_mfma_f32_16x16x32_bf16 v[134:137], v[220:223], v[204:207], v[134:137]
	v_mfma_f32_16x16x32_bf16 v[130:133], v[224:227], v[204:207], v[130:133]
	ds_read_b128 v[204:207], v0 offset:10240
	s_waitcnt lgkmcnt(6)
	v_mfma_f32_16x16x32_bf16 v[126:129], v[212:215], v[208:211], v[126:129]
	v_mfma_f32_16x16x32_bf16 v[122:125], v[216:219], v[208:211], v[122:125]
	v_mfma_f32_16x16x32_bf16 v[118:121], v[220:223], v[208:211], v[118:121]
	v_mfma_f32_16x16x32_bf16 v[114:117], v[224:227], v[208:211], v[114:117]
	ds_read_b128 v[208:211], v0 offset:12288
	s_waitcnt lgkmcnt(5)
	v_mfma_f32_16x16x32_bf16 v[110:113], v[212:215], v[238:241], v[110:113]
	v_mfma_f32_16x16x32_bf16 v[106:109], v[216:219], v[238:241], v[106:109]
	v_mfma_f32_16x16x32_bf16 v[102:105], v[220:223], v[238:241], v[102:105]
	v_mfma_f32_16x16x32_bf16 v[98:101], v[224:227], v[238:241], v[98:101]
	ds_read_b128 v[238:241], v0 offset:14336
	s_waitcnt lgkmcnt(4)
	v_mfma_f32_16x16x32_bf16 v[94:97], v[212:215], v[162:165], v[94:97]
	v_mfma_f32_16x16x32_bf16 v[90:93], v[216:219], v[162:165], v[90:93]
	v_mfma_f32_16x16x32_bf16 v[86:89], v[220:223], v[162:165], v[86:89]
	v_mfma_f32_16x16x32_bf16 v[82:85], v[224:227], v[162:165], v[82:85]
	s_waitcnt lgkmcnt(0)
	s_setprio 0
	s_barrier
; template <int MI, int NJ> ...
;     ...
;   for (int kt = 0; kt < nk; ++kt) {
;     const int buf = kt & 1;
;     {
;       G8STORE(buf ^ 1);
;       const u16* ga_ = (kt + 2 < nk) ? Ag + (kt + 2) * 64 : Ag + nAoff;
;       const u16* gb_ = (kt + 2 < nk) ? Bg + (kt + 2) * 64 : Bg + nBoff;
;       G8LOADP(ga_, gb_);
;     }
;     __builtin_amdgcn_sched_barrier(0);
;     __builtin_amdgcn_s_setprio(1);
;     const u16* a = ra_ + buf * AROWS * 64;
;     const u16* b = rb_ + buf * BROWS * 64;
; #pragma unroll
;     for (int ks = 0; ks < 2; ++ks) {
;       const u16* a_ = ks ? a + dsw : a;
;       const u16* b_ = ks ? b + dsw : b;
;       bf16x8 bfr[NJ];
; #pragma unroll
;       for (int j = 0; j < NJ; ++j) bfr[j] = *(const bf16x8*)(b_ + j * 16 * 64);
; #pragma unroll
;       for (int ih = 0; ih < MI / 4; ++ih) {
;         bf16x8 af[4];
; #pragma unroll
;         for (int i = 0; i < 4; ++i) af[i] = *(const bf16x8*)(a_ + (ih * 4 + i) * 16 * 64);
; #pragma unroll
;         for (int i = 0; i < 4; ++i)
; #pragma unroll
;           for (int j = 0; j < NJ; ++j) acc[ih * 4 + i][j] = mfma16(af[i], bfr[j], acc[ih * 4 + i][j]);
;       }
;     }
;     __builtin_amdgcn_s_setprio(0);
;     __builtin_amdgcn_sched_barrier(0);
;     __syncthreads();
;   }
; __device__ __forceinline__ void phase_win(const Params& p, int part, u16* smem, volatile LAS unsigned* vb_) {
;     ...
; #pragma unroll
;     for (int i = 0; i < 8; ++i)
; #pragma unroll
;       for (int j = 0; j < 4; ++j)
; #pragma unroll
;         for (int r = 0; r < 4; ++r)
;           smem[(wm * 128 + i * 16 + (lane >> 4) * 4 + r) * 264 + wn * 64 + j * 16 + (lane & 15)] = f2bf(acc[i][j][r]);
	s_add_i32 s37, s37, 1
	s_add_u32 s20, s20, 64
	s_addc_u32 s21, s21, 0
	s_addk_i32 s11, 0x4000
	s_and_b32 s38, s11, 0x4000
	s_xor_b32 s39, s38, 0x4000
	s_lshl_b32 s39, s39, 1
	v_add_u32_e32 v228, s39, v185
	v_add_u32_e32 v229, s39, v186
	s_cmp_lt_u32 s37, 14
	s_cselect_b32 s49, s21, s13
	s_cselect_b32 s48, s20, s12
	s_cselect_b32 s51, s21, s47
	s_cselect_b32 s50, s20, s46
	s_lshl_b64 s[48:49], s[48:49], 1
	s_lshl_b64 s[50:51], s[50:51], 1
	s_add_u32 s52, s62, s48
	s_addc_u32 s53, s63, s49
	s_add_u32 s66, s64, s50
	s_addc_u32 s67, s65, s51
	s_lshl_b32 s38, s38, 1
	v_add_u32_e32 v0, s38, v187
	v_add_u32_e32 v191, s38, v188
	s_setprio 1
	ds_read_b128 v[166:169], v191
	ds_read_b128 v[162:165], v0
	ds_read_b128 v[170:173], v191 offset:2048
	ds_read_b128 v[192:195], v191 offset:4096
	ds_read_b128 v[196:199], v191 offset:6144
	v_mfma_f32_16x16x32_bf16 v[78:81], v[212:215], v[204:207], v[78:81]
	v_mfma_f32_16x16x32_bf16 v[74:77], v[216:219], v[204:207], v[74:77]
	v_mfma_f32_16x16x32_bf16 v[70:73], v[220:223], v[204:207], v[70:73]
	v_mfma_f32_16x16x32_bf16 v[66:69], v[224:227], v[204:207], v[66:69]
	ds_read_b128 v[204:207], v0 offset:2048
	v_mfma_f32_16x16x32_bf16 v[62:65], v[212:215], v[208:211], v[62:65]
	v_mfma_f32_16x16x32_bf16 v[58:61], v[216:219], v[208:211], v[58:61]
	v_mfma_f32_16x16x32_bf16 v[54:57], v[220:223], v[208:211], v[54:57]
	v_mfma_f32_16x16x32_bf16 v[50:53], v[224:227], v[208:211], v[50:53]
	ds_read_b128 v[208:211], v0 offset:4096
	v_mfma_f32_16x16x32_bf16 v[46:49], v[212:215], v[238:241], v[46:49]
	v_mfma_f32_16x16x32_bf16 v[42:45], v[216:219], v[238:241], v[42:45]
	v_mfma_f32_16x16x32_bf16 v[38:41], v[220:223], v[238:241], v[38:41]
	v_mfma_f32_16x16x32_bf16 v[34:37], v[224:227], v[238:241], v[34:37]
	ds_read_b128 v[238:241], v0 offset:6144
	v_add_u32_e32 v191, v191, v190
	s_setprio 0
	s_cmpk_lg_i32 s20, 0x480
	s_cbranch_scc1 .LBB0_470
	v_and_b32_e32 v228, 15, v175
	v_bfe_u32 v229, v175, 8, 1
	v_lshl_or_b32 v228, v229, 7, v228
	v_mul_u32_u24_e32 v228, 0x210, v228
	v_bfe_u32 v229, v175, 6, 2
	v_lshl_add_u32 v228, v229, 7, v228
	v_bfe_u32 v229, v175, 4, 2
	v_lshl_add_u32 v228, v229, 3, v228
	v_cvt_pk_bf16_f32 v158, v158, v159
	v_cvt_pk_bf16_f32 v159, v160, v161
	v_cvt_pk_bf16_f32 v154, v154, v155
	v_cvt_pk_bf16_f32 v155, v156, v157
	v_cvt_pk_bf16_f32 v150, v150, v151
	v_cvt_pk_bf16_f32 v151, v152, v153
	v_cvt_pk_bf16_f32 v146, v146, v147
	v_cvt_pk_bf16_f32 v147, v148, v149
	ds_write_b64 v228, v[158:159]
	ds_write_b64 v228, v[154:155] offset:32
	ds_write_b64 v228, v[150:151] offset:64
	ds_write_b64 v228, v[146:147] offset:96
	v_cvt_pk_bf16_f32 v142, v142, v143
	v_cvt_pk_bf16_f32 v143, v144, v145
	v_cvt_pk_bf16_f32 v138, v138, v139
	v_cvt_pk_bf16_f32 v139, v140, v141
	v_cvt_pk_bf16_f32 v134, v134, v135
	v_cvt_pk_bf16_f32 v135, v136, v137
	v_cvt_pk_bf16_f32 v130, v130, v131
	v_cvt_pk_bf16_f32 v131, v132, v133
	ds_write_b64 v228, v[142:143] offset:8448
	ds_write_b64 v228, v[138:139] offset:8480
	ds_write_b64 v228, v[134:135] offset:8512
	ds_write_b64 v228, v[130:131] offset:8544
	v_cvt_pk_bf16_f32 v126, v126, v127
	v_cvt_pk_bf16_f32 v127, v128, v129
	v_cvt_pk_bf16_f32 v122, v122, v123
	v_cvt_pk_bf16_f32 v123, v124, v125
	v_cvt_pk_bf16_f32 v118, v118, v119
	v_cvt_pk_bf16_f32 v119, v120, v121
	v_cvt_pk_bf16_f32 v114, v114, v115
	v_cvt_pk_bf16_f32 v115, v116, v117
	ds_write_b64 v228, v[126:127] offset:16896
	ds_write_b64 v228, v[122:123] offset:16928
	ds_write_b64 v228, v[118:119] offset:16960
	ds_write_b64 v228, v[114:115] offset:16992
	v_cvt_pk_bf16_f32 v110, v110, v111
	v_cvt_pk_bf16_f32 v111, v112, v113
	v_cvt_pk_bf16_f32 v106, v106, v107
	v_cvt_pk_bf16_f32 v107, v108, v109
	v_cvt_pk_bf16_f32 v102, v102, v103
	v_cvt_pk_bf16_f32 v103, v104, v105
	v_cvt_pk_bf16_f32 v98, v98, v99
	v_cvt_pk_bf16_f32 v99, v100, v101
	ds_write_b64 v228, v[110:111] offset:25344
	ds_write_b64 v228, v[106:107] offset:25376
	ds_write_b64 v228, v[102:103] offset:25408
	ds_write_b64 v228, v[98:99] offset:25440
	v_cvt_pk_bf16_f32 v94, v94, v95
	v_cvt_pk_bf16_f32 v95, v96, v97
	v_cvt_pk_bf16_f32 v90, v90, v91
	v_cvt_pk_bf16_f32 v91, v92, v93
	v_cvt_pk_bf16_f32 v86, v86, v87
	v_cvt_pk_bf16_f32 v87, v88, v89
	v_cvt_pk_bf16_f32 v82, v82, v83
	v_cvt_pk_bf16_f32 v83, v84, v85
	ds_write_b64 v228, v[94:95] offset:33792
	ds_write_b64 v228, v[90:91] offset:33824
	ds_write_b64 v228, v[86:87] offset:33856
	ds_write_b64 v228, v[82:83] offset:33888
	v_cvt_pk_bf16_f32 v78, v78, v79
	v_cvt_pk_bf16_f32 v79, v80, v81
	v_cvt_pk_bf16_f32 v74, v74, v75
	v_cvt_pk_bf16_f32 v75, v76, v77
	v_cvt_pk_bf16_f32 v70, v70, v71
	v_cvt_pk_bf16_f32 v71, v72, v73
	v_cvt_pk_bf16_f32 v66, v66, v67
	v_cvt_pk_bf16_f32 v67, v68, v69
	ds_write_b64 v228, v[78:79] offset:42240
	ds_write_b64 v228, v[74:75] offset:42272
	ds_write_b64 v228, v[70:71] offset:42304
	ds_write_b64 v228, v[66:67] offset:42336
	v_cvt_pk_bf16_f32 v62, v62, v63
	v_cvt_pk_bf16_f32 v63, v64, v65
	v_cvt_pk_bf16_f32 v58, v58, v59
	v_cvt_pk_bf16_f32 v59, v60, v61
	v_cvt_pk_bf16_f32 v54, v54, v55
	v_cvt_pk_bf16_f32 v55, v56, v57
	v_cvt_pk_bf16_f32 v50, v50, v51
	v_cvt_pk_bf16_f32 v51, v52, v53
	ds_write_b64 v228, v[62:63] offset:50688
	ds_write_b64 v228, v[58:59] offset:50720
	ds_write_b64 v228, v[54:55] offset:50752
	ds_write_b64 v228, v[50:51] offset:50784
	v_cvt_pk_bf16_f32 v46, v46, v47
	v_cvt_pk_bf16_f32 v47, v48, v49
	v_cvt_pk_bf16_f32 v42, v42, v43
	v_cvt_pk_bf16_f32 v43, v44, v45
	v_cvt_pk_bf16_f32 v38, v38, v39
	v_cvt_pk_bf16_f32 v39, v40, v41
	v_cvt_pk_bf16_f32 v34, v34, v35
	v_cvt_pk_bf16_f32 v35, v36, v37
	ds_write_b64 v228, v[46:47] offset:59136
	ds_write_b64 v228, v[42:43] offset:59168
	ds_write_b64 v228, v[38:39] offset:59200
	ds_write_b64 v228, v[34:35] offset:59232
	v_mov_b32_e32 v43, v175
	s_waitcnt lgkmcnt(0)
	s_barrier
; #define RTID opaque_tid()
; __device__ __forceinline__ void phase_win(const Params& p, int part, u16* smem, volatile LAS unsigned* vb_) {
;     ...
;     const int tid2 = RTID;
; #pragma unroll
;     for (int k = 0; k < 16; ++k) {
;       const int c = tid2 + 512 * k;
;       const int row = c >> 5, ch = c & 31;
;       const uint4 v = *(const uint4*)(smem + row * 264 + ch * 8);
;       u16* d_ = (ch < 16) ? dstA : dstB;
;       const int l_ = (ch < 16) ? ldA : ldB;
;       *(uint4*)(d_ + (size_t)(mt * 256 + row) * l_ + (ch & 15) * 8) = v;
;     }
;     __syncthreads();
	s_mov_b32 s38, s36
	v_and_b32_e32 v0, 31, v43
	v_lshlrev_b32_e32 v42, 4, v0
	v_cmp_gt_u32_e32 vcc, 16, v0
	v_mov_b32_e32 v0, 0x100
	s_nop 0
	v_cndmask_b32_e64 v0, v0, 0, vcc
	v_lshl_add_u64 v[34:35], s[44:45], 0, v[0:1]
	v_lshlrev_b32_e32 v0, 4, v43
	v_and_b32_e32 v0, 0xf0, v0
	v_lshl_add_u64 v[44:45], v[34:35], 0, v[0:1]
	v_ashrrev_i32_e32 v0, 5, v43
	v_mad_u64_u32 v[34:35], s[12:13], v0, s2, v[42:43]
	v_add_u32_e32 v0, s10, v0
	ds_read_b128 v[34:37], v34
	v_ashrrev_i32_e32 v38, 31, v0
	v_mul_lo_u32 v40, s0, v38
	v_mul_lo_u32 v41, s1, v0
	v_mad_u64_u32 v[38:39], s[12:13], s0, v0, 0
	v_add_u32_e32 v0, 0x200, v43
	v_add3_u32 v39, v39, v40, v41
	v_ashrrev_i32_e32 v0, 5, v0
	v_lshl_add_u64 v[46:47], v[38:39], 1, v[44:45]
	v_mad_u64_u32 v[38:39], s[12:13], v0, s2, v[42:43]
	ds_read_b128 v[38:41], v38
	v_add_u32_e32 v0, s10, v0
	s_waitcnt lgkmcnt(1)
	global_store_dwordx4 v[46:47], v[34:37], off
	s_and_b64 vcc, exec, s[42:43]
	s_nop 0
	v_ashrrev_i32_e32 v34, 31, v0
	v_mul_lo_u32 v36, s0, v34
	v_mul_lo_u32 v37, s1, v0
	v_mad_u64_u32 v[34:35], s[12:13], s0, v0, 0
	v_add3_u32 v35, v35, v36, v37
	v_add_u32_e32 v0, 0x400, v43
	v_lshl_add_u64 v[34:35], v[34:35], 1, v[44:45]
	v_ashrrev_i32_e32 v0, 5, v0
	s_waitcnt lgkmcnt(0)
	global_store_dwordx4 v[34:35], v[38:41], off
	v_mad_u64_u32 v[34:35], s[12:13], v0, s2, v[42:43]
	v_add_u32_e32 v0, s10, v0
	ds_read_b128 v[34:37], v34
	v_ashrrev_i32_e32 v38, 31, v0
	v_mul_lo_u32 v40, s0, v38
	v_mul_lo_u32 v41, s1, v0
	v_mad_u64_u32 v[38:39], s[12:13], s0, v0, 0
	v_add_u32_e32 v0, 0x600, v43
	v_add3_u32 v39, v39, v40, v41
	v_ashrrev_i32_e32 v0, 5, v0
	v_lshl_add_u64 v[46:47], v[38:39], 1, v[44:45]
	v_mad_u64_u32 v[38:39], s[12:13], v0, s2, v[42:43]
	ds_read_b128 v[38:41], v38
	v_add_u32_e32 v0, s10, v0
	s_waitcnt lgkmcnt(1)
	global_store_dwordx4 v[46:47], v[34:37], off
	s_nop 1
	v_ashrrev_i32_e32 v34, 31, v0
	v_mul_lo_u32 v36, s0, v34
	v_mul_lo_u32 v37, s1, v0
	v_mad_u64_u32 v[34:35], s[12:13], s0, v0, 0
	v_add3_u32 v35, v35, v36, v37
	v_add_u32_e32 v0, 0x800, v43
	v_lshl_add_u64 v[34:35], v[34:35], 1, v[44:45]
	v_ashrrev_i32_e32 v0, 5, v0
	s_waitcnt lgkmcnt(0)
	global_store_dwordx4 v[34:35], v[38:41], off
	v_mad_u64_u32 v[34:35], s[12:13], v0, s2, v[42:43]
	v_add_u32_e32 v0, s10, v0
	ds_read_b128 v[34:37], v34
	v_ashrrev_i32_e32 v38, 31, v0
	v_mul_lo_u32 v40, s0, v38
	v_mul_lo_u32 v41, s1, v0
	v_mad_u64_u32 v[38:39], s[12:13], s0, v0, 0
	v_add_u32_e32 v0, 0xa00, v43
	v_add3_u32 v39, v39, v40, v41
	v_ashrrev_i32_e32 v0, 5, v0
	v_lshl_add_u64 v[46:47], v[38:39], 1, v[44:45]
	v_mad_u64_u32 v[38:39], s[12:13], v0, s2, v[42:43]
	ds_read_b128 v[38:41], v38
	v_add_u32_e32 v0, s10, v0
	s_waitcnt lgkmcnt(1)
	global_store_dwordx4 v[46:47], v[34:37], off
	s_nop 1
	v_ashrrev_i32_e32 v34, 31, v0
	v_mul_lo_u32 v36, s0, v34
	v_mul_lo_u32 v37, s1, v0
	v_mad_u64_u32 v[34:35], s[12:13], s0, v0, 0
	v_add3_u32 v35, v35, v36, v37
	v_add_u32_e32 v0, 0xc00, v43
	v_lshl_add_u64 v[34:35], v[34:35], 1, v[44:45]
	v_ashrrev_i32_e32 v0, 5, v0
	s_waitcnt lgkmcnt(0)
	global_store_dwordx4 v[34:35], v[38:41], off
	v_mad_u64_u32 v[34:35], s[12:13], v0, s2, v[42:43]
	v_add_u32_e32 v0, s10, v0
	ds_read_b128 v[34:37], v34
	v_ashrrev_i32_e32 v38, 31, v0
	v_mul_lo_u32 v40, s0, v38
	v_mul_lo_u32 v41, s1, v0
	v_mad_u64_u32 v[38:39], s[12:13], s0, v0, 0
	v_add_u32_e32 v0, 0xe00, v43
	v_add3_u32 v39, v39, v40, v41
	v_ashrrev_i32_e32 v0, 5, v0
	v_lshl_add_u64 v[46:47], v[38:39], 1, v[44:45]
	v_mad_u64_u32 v[38:39], s[12:13], v0, s2, v[42:43]
	ds_read_b128 v[38:41], v38
	v_add_u32_e32 v0, s10, v0
	s_waitcnt lgkmcnt(1)
	global_store_dwordx4 v[46:47], v[34:37], off
	s_nop 1
	v_ashrrev_i32_e32 v34, 31, v0
	v_mul_lo_u32 v36, s0, v34
	v_mul_lo_u32 v37, s1, v0
	v_mad_u64_u32 v[34:35], s[12:13], s0, v0, 0
	v_add3_u32 v35, v35, v36, v37
	v_add_u32_e32 v0, 0x1000, v43
	v_lshl_add_u64 v[34:35], v[34:35], 1, v[44:45]
	v_ashrrev_i32_e32 v0, 5, v0
	s_waitcnt lgkmcnt(0)
; #define RTID opaque_tid()
; __device__ __forceinline__ void phase_win(const Params& p, int part, u16* smem, volatile LAS unsigned* vb_) {
;     ...
;     const int tid2 = RTID;
; #pragma unroll
;     for (int k = 0; k < 16; ++k) {
;       const int c = tid2 + 512 * k;
;       const int row = c >> 5, ch = c & 31;
;       const uint4 v = *(const uint4*)(smem + row * 264 + ch * 8);
;       u16* d_ = (ch < 16) ? dstA : dstB;
;       const int l_ = (ch < 16) ? ldA : ldB;
;       *(uint4*)(d_ + (size_t)(mt * 256 + row) * l_ + (ch & 15) * 8) = v;
;     }
;     __syncthreads();
	global_store_dwordx4 v[34:35], v[38:41], off
	v_mad_u64_u32 v[34:35], s[12:13], v0, s2, v[42:43]
	v_add_u32_e32 v0, s10, v0
	ds_read_b128 v[34:37], v34
	v_ashrrev_i32_e32 v38, 31, v0
	v_mul_lo_u32 v40, s0, v38
	v_mul_lo_u32 v41, s1, v0
	v_mad_u64_u32 v[38:39], s[12:13], s0, v0, 0
	v_add_u32_e32 v0, 0x1200, v43
	v_add3_u32 v39, v39, v40, v41
	v_ashrrev_i32_e32 v0, 5, v0
	v_lshl_add_u64 v[46:47], v[38:39], 1, v[44:45]
	v_mad_u64_u32 v[38:39], s[12:13], v0, s2, v[42:43]
	ds_read_b128 v[38:41], v38
	v_add_u32_e32 v0, s10, v0
	s_waitcnt lgkmcnt(1)
	global_store_dwordx4 v[46:47], v[34:37], off
	s_nop 1
	v_ashrrev_i32_e32 v34, 31, v0
	v_mul_lo_u32 v36, s0, v34
	v_mul_lo_u32 v37, s1, v0
	v_mad_u64_u32 v[34:35], s[12:13], s0, v0, 0
	v_add3_u32 v35, v35, v36, v37
	v_add_u32_e32 v0, 0x1400, v43
	v_lshl_add_u64 v[34:35], v[34:35], 1, v[44:45]
	v_ashrrev_i32_e32 v0, 5, v0
	s_waitcnt lgkmcnt(0)
	global_store_dwordx4 v[34:35], v[38:41], off
	v_mad_u64_u32 v[34:35], s[12:13], v0, s2, v[42:43]
	v_add_u32_e32 v0, s10, v0
	ds_read_b128 v[34:37], v34
	v_ashrrev_i32_e32 v38, 31, v0
	v_mul_lo_u32 v40, s0, v38
	v_mul_lo_u32 v41, s1, v0
	v_mad_u64_u32 v[38:39], s[12:13], s0, v0, 0
	v_add_u32_e32 v0, 0x1600, v43
	v_add3_u32 v39, v39, v40, v41
	v_ashrrev_i32_e32 v0, 5, v0
	v_lshl_add_u64 v[46:47], v[38:39], 1, v[44:45]
	v_mad_u64_u32 v[38:39], s[12:13], v0, s2, v[42:43]
	ds_read_b128 v[38:41], v38
	v_add_u32_e32 v0, s10, v0
	s_waitcnt lgkmcnt(1)
	global_store_dwordx4 v[46:47], v[34:37], off
	s_nop 1
	v_ashrrev_i32_e32 v34, 31, v0
	v_mul_lo_u32 v36, s0, v34
	v_mul_lo_u32 v37, s1, v0
	v_mad_u64_u32 v[34:35], s[12:13], s0, v0, 0
	v_add3_u32 v35, v35, v36, v37
	v_add_u32_e32 v0, 0x1800, v43
	v_lshl_add_u64 v[34:35], v[34:35], 1, v[44:45]
	v_ashrrev_i32_e32 v0, 5, v0
	s_waitcnt lgkmcnt(0)
	global_store_dwordx4 v[34:35], v[38:41], off
	v_mad_u64_u32 v[34:35], s[12:13], v0, s2, v[42:43]
	v_add_u32_e32 v0, s10, v0
	ds_read_b128 v[34:37], v34
	v_ashrrev_i32_e32 v38, 31, v0
	v_mul_lo_u32 v40, s0, v38
	v_mul_lo_u32 v41, s1, v0
	v_mad_u64_u32 v[38:39], s[12:13], s0, v0, 0
	v_add_u32_e32 v0, 0x1a00, v43
	v_add3_u32 v39, v39, v40, v41
	v_ashrrev_i32_e32 v0, 5, v0
	v_lshl_add_u64 v[46:47], v[38:39], 1, v[44:45]
	v_mad_u64_u32 v[38:39], s[12:13], v0, s2, v[42:43]
	ds_read_b128 v[38:41], v38
	v_add_u32_e32 v0, s10, v0
	s_waitcnt lgkmcnt(1)
	global_store_dwordx4 v[46:47], v[34:37], off
	s_nop 1
	v_ashrrev_i32_e32 v34, 31, v0
	v_mul_lo_u32 v36, s0, v34
	v_mul_lo_u32 v37, s1, v0
	v_mad_u64_u32 v[34:35], s[12:13], s0, v0, 0
	v_add3_u32 v35, v35, v36, v37
	v_add_u32_e32 v0, 0x1c00, v43
	v_lshl_add_u64 v[34:35], v[34:35], 1, v[44:45]
	v_ashrrev_i32_e32 v0, 5, v0
	s_waitcnt lgkmcnt(0)
	global_store_dwordx4 v[34:35], v[38:41], off
	v_mad_u64_u32 v[34:35], s[12:13], v0, s2, v[42:43]
	v_add_u32_e32 v0, s10, v0
	ds_read_b128 v[34:37], v34
	v_ashrrev_i32_e32 v38, 31, v0
	v_mul_lo_u32 v40, s0, v38
	v_mul_lo_u32 v41, s1, v0
	v_mad_u64_u32 v[38:39], s[12:13], s0, v0, 0
	v_add_u32_e32 v0, 0x1e00, v43
	v_add3_u32 v39, v39, v40, v41
	v_ashrrev_i32_e32 v0, 5, v0
	v_lshl_add_u64 v[46:47], v[38:39], 1, v[44:45]
	v_mad_u64_u32 v[38:39], s[12:13], v0, s2, v[42:43]
	ds_read_b128 v[38:41], v38
	v_add_u32_e32 v0, s10, v0
	s_waitcnt lgkmcnt(1)
	global_store_dwordx4 v[46:47], v[34:37], off
	s_mov_b64 s[12:13], -1
	s_nop 0
	v_ashrrev_i32_e32 v34, 31, v0
	v_mul_lo_u32 v36, s0, v34
	v_mul_lo_u32 v37, s1, v0
	v_mad_u64_u32 v[34:35], s[0:1], s0, v0, 0
	v_add3_u32 v35, v35, v36, v37
	v_lshl_add_u64 v[34:35], v[34:35], 1, v[44:45]
	s_waitcnt lgkmcnt(0)
	global_store_dwordx4 v[34:35], v[38:41], off
	s_barrier
	s_cbranch_vccz .LBB0_441

; #define ZERO_ACC8(acc, NJ_)                             \
;   _Pragma("unroll") for (int i_ = 0; i_ < 8; ++i_)      \
;   _Pragma("unroll") for (int j_ = 0; j_ < (NJ_); ++j_) { acc[i_][j_] = (f32x4){0.f, 0.f, 0.f, 0.f}; }
; template <int MI, int NJ> ...
;     ...
;   if (!pre) G8LOADP(Ag, Bg);
;   G8STORE(0);
;   {
;     const u16* ga_ = (1 < nk) ? Ag + 64 : Ag + nAoff;
;     const u16* gb_ = (1 < nk) ? Bg + 64 : Bg + nBoff;
;     G8LOADP(ga_, gb_);
;   }
;   __syncthreads();
;   const int sw0 = ((lane >> 4) ^ (lane & 7)) * 8;
;   const int dsw = (sw0 ^ 32) - sw0;
;   const u16* ra_ = sA + (wm * (16 * MI) + (lane & 15)) * 64 + sw0;
;   const u16* rb_ = sB + (wn * (16 * NJ) + (lane & 15)) * 64 + sw0;
;   for (int kt = 0; kt < nk; ++kt) {
;     const int buf = kt & 1;
;     {
;       G8STORE(buf ^ 1);
;       const u16* ga_ = (kt + 2 < nk) ? Ag + (kt + 2) * 64 : Ag + nAoff;
;       const u16* gb_ = (kt + 2 < nk) ? Bg + (kt + 2) * 64 : Bg + nBoff;
;       G8LOADP(ga_, gb_);
;     }
;     __builtin_amdgcn_sched_barrier(0);
;     __builtin_amdgcn_s_setprio(1);
;     const u16* a = ra_ + buf * AROWS * 64;
;     const u16* b = rb_ + buf * BROWS * 64;
; __device__ __forceinline__ void phase_gemm_f32(const u16* A, const u16* Bt, int K, u16* out, u16* smem,
;                                                volatile LAS unsigned* vb_) {
;     ...
;   for (int lt = vb >> 3; lt < 8 * 4; lt += step) {
;     const int nt = lt >> 3, mt = (vb & 7) * 8 + (lt & 7);
;     const int ltn = (lt + step < 8 * 4) ? lt + step : lt;
;     f32x4 acc[8][4];
;     ZERO_ACC8(acc, 4);
;     gemm8<8, 4>(acc, G8REGS_ARGS, pre, A, K, Bt, K, 0, K, mt * 256, nt * 256, ((vb & 7) * 8 + (ltn & 7)) * 256, (ltn >> 3) * 256, 0, smem, tid);
.LBB0_480:
	s_waitcnt vmcnt(5)
	ds_write_b128 v185, v[10:13]
	ds_write_b128 v185, v[2:5] offset:8192
	ds_write_b128 v185, v[6:9] offset:16384
	s_waitcnt vmcnt(3)
	ds_write_b128 v185, v[14:17] offset:24576
	ds_write_b128 v186, v[18:21]
	s_waitcnt vmcnt(2)
	ds_write_b128 v186, v[42:45] offset:8192
	s_waitcnt vmcnt(1)
	ds_write_b128 v186, v[62:65] offset:16384
	s_waitcnt vmcnt(0)
	ds_write_b128 v186, v[74:77] offset:24576
	global_load_dwordx4 v[10:13], v234, s[62:63] offset:128
	global_load_dwordx4 v[2:5], v235, s[62:63] offset:128
	global_load_dwordx4 v[6:9], v236, s[62:63] offset:128
	global_load_dwordx4 v[14:17], v237, s[62:63] offset:128
	global_load_dwordx4 v[18:21], v234, s[64:65] offset:128
	global_load_dwordx4 v[42:45], v235, s[64:65] offset:128
	global_load_dwordx4 v[62:65], v236, s[64:65] offset:128
	global_load_dwordx4 v[74:77], v237, s[64:65] offset:128
	s_add_i32 s36, s37, s70
	s_cmp_gt_i32 s36, 31
	s_cselect_b64 s[40:41], -1, 0
	s_cmp_lt_i32 s36, 32
	s_cselect_b32 s12, s36, s37
	s_and_b32 s13, s12, 7
	s_lshl_b32 s12, s12, 5
	s_and_b32 s37, s12, 0xffffff00
	s_sub_i32 s12, s13, s38
	s_lshl_b32 s13, s12, 8
	s_sub_i32 s38, s37, s42
	v_mov_b32_e32 v22, 0
	s_mul_hi_i32 s12, s13, s10
	s_mul_i32 s13, s13, s10
	s_mul_hi_i32 s37, s38, s10
	s_mul_i32 s38, s38, s10
	s_movk_i32 s39, 0x80
	s_mov_b32 s43, 0
	s_mov_b32 s44, 0
	v_mov_b32_e32 v23, v22
	v_mov_b32_e32 v24, v22
	v_mov_b32_e32 v25, v22
	v_mov_b32_e32 v26, v22
	v_mov_b32_e32 v27, v22
	v_mov_b32_e32 v28, v22
	v_mov_b32_e32 v29, v22
	v_mov_b32_e32 v30, v22
	v_mov_b32_e32 v31, v22
	v_mov_b32_e32 v32, v22
	v_mov_b32_e32 v33, v22
	v_mov_b32_e32 v34, v22
	v_mov_b32_e32 v35, v22
	v_mov_b32_e32 v36, v22
	v_mov_b32_e32 v37, v22
	v_mov_b32_e32 v38, v22
	v_mov_b32_e32 v39, v22
	v_mov_b32_e32 v40, v22
	v_mov_b32_e32 v41, v22
	v_mov_b32_e32 v46, v22
	v_mov_b32_e32 v47, v22
	v_mov_b32_e32 v48, v22
	v_mov_b32_e32 v49, v22
	v_mov_b32_e32 v50, v22
	v_mov_b32_e32 v51, v22
	v_mov_b32_e32 v52, v22
	v_mov_b32_e32 v53, v22
	v_mov_b32_e32 v54, v22
	v_mov_b32_e32 v55, v22
	v_mov_b32_e32 v56, v22
	v_mov_b32_e32 v57, v22
	v_mov_b32_e32 v58, v22
	v_mov_b32_e32 v59, v22
	v_mov_b32_e32 v60, v22
	v_mov_b32_e32 v61, v22
	v_mov_b32_e32 v66, v22
	v_mov_b32_e32 v67, v22
	v_mov_b32_e32 v68, v22
	v_mov_b32_e32 v69, v22
	v_mov_b32_e32 v70, v22
	v_mov_b32_e32 v71, v22
	v_mov_b32_e32 v72, v22
	v_mov_b32_e32 v73, v22
	v_mov_b32_e32 v78, v22
	v_mov_b32_e32 v79, v22
	v_mov_b32_e32 v80, v22
	v_mov_b32_e32 v81, v22
	v_mov_b32_e32 v82, v22
	v_mov_b32_e32 v83, v22
	v_mov_b32_e32 v84, v22
	v_mov_b32_e32 v85, v22
	v_mov_b32_e32 v86, v22
	v_mov_b32_e32 v87, v22
	v_mov_b32_e32 v88, v22
	v_mov_b32_e32 v89, v22
	v_mov_b32_e32 v90, v22
	v_mov_b32_e32 v91, v22
	v_mov_b32_e32 v92, v22
	v_mov_b32_e32 v93, v22
	v_mov_b32_e32 v94, v22
	v_mov_b32_e32 v95, v22
	v_mov_b32_e32 v96, v22
	v_mov_b32_e32 v97, v22
	v_mov_b32_e32 v98, v22
	v_mov_b32_e32 v99, v22
	v_mov_b32_e32 v100, v22
	v_mov_b32_e32 v101, v22
	v_mov_b32_e32 v102, v22
	v_mov_b32_e32 v103, v22
	v_mov_b32_e32 v104, v22
	v_mov_b32_e32 v105, v22
	v_mov_b32_e32 v106, v22
	v_mov_b32_e32 v107, v22
	v_mov_b32_e32 v108, v22
	v_mov_b32_e32 v109, v22
	v_mov_b32_e32 v110, v22
	v_mov_b32_e32 v111, v22
	v_mov_b32_e32 v112, v22
	v_mov_b32_e32 v113, v22
	v_mov_b32_e32 v114, v22
	v_mov_b32_e32 v115, v22
	v_mov_b32_e32 v116, v22
	v_mov_b32_e32 v117, v22
	v_mov_b32_e32 v118, v22
	v_mov_b32_e32 v119, v22
	v_mov_b32_e32 v120, v22
	v_mov_b32_e32 v121, v22
	v_mov_b32_e32 v122, v22
	v_mov_b32_e32 v123, v22
	v_mov_b32_e32 v124, v22
	v_mov_b32_e32 v125, v22
	v_mov_b32_e32 v126, v22
	v_mov_b32_e32 v127, v22
	v_mov_b32_e32 v128, v22
	v_mov_b32_e32 v129, v22
	v_mov_b32_e32 v130, v22
	v_mov_b32_e32 v131, v22
	v_mov_b32_e32 v132, v22
	v_mov_b32_e32 v133, v22
	v_mov_b32_e32 v134, v22
	v_mov_b32_e32 v135, v22
	v_mov_b32_e32 v136, v22
	v_mov_b32_e32 v137, v22
	v_mov_b32_e32 v138, v22
	v_mov_b32_e32 v139, v22
	v_mov_b32_e32 v140, v22
	v_mov_b32_e32 v141, v22
	v_mov_b32_e32 v142, v22
	v_mov_b32_e32 v143, v22
	v_mov_b32_e32 v144, v22
	v_mov_b32_e32 v145, v22
	v_mov_b32_e32 v146, v22
	v_mov_b32_e32 v147, v22
	v_mov_b32_e32 v148, v22
	v_mov_b32_e32 v149, v22
	v_mov_b32_e32 v150, v22
	v_mov_b32_e32 v151, v22
	v_mov_b32_e32 v152, v22
	v_mov_b32_e32 v153, v22
	v_mov_b32_e32 v154, v22
	v_mov_b32_e32 v155, v22
	v_mov_b32_e32 v156, v22
	v_mov_b32_e32 v157, v22
	v_mov_b32_e32 v158, v22
	v_mov_b32_e32 v159, v22
	v_mov_b32_e32 v160, v22
	v_mov_b32_e32 v161, v22
	s_waitcnt lgkmcnt(0)
	s_barrier
	s_and_b32 s45, s43, 0x4000
	s_xor_b32 s46, s45, 0x4000
	s_lshl_b32 s46, s46, 1
	v_add_u32_e32 v228, s46, v185
	v_add_u32_e32 v229, s46, v186
	s_add_i32 s46, s44, 2
	s_cmp_lt_u32 s46, s21
	s_cselect_b32 s47, 0, s12
	s_cselect_b32 s46, s39, s13
	s_cselect_b32 s49, 0, s37
	s_cselect_b32 s48, s39, s38
	s_lshl_b64 s[46:47], s[46:47], 1
	s_lshl_b64 s[48:49], s[48:49], 1
	s_add_u32 s50, s62, s46
	s_addc_u32 s51, s63, s47
	s_add_u32 s52, s64, s48
	s_addc_u32 s53, s65, s49
	s_lshl_b32 s45, s45, 1
	v_add_u32_e32 v0, s45, v187
	v_add_u32_e32 v191, s45, v188
	ds_read_b128 v[166:169], v191
	ds_read_b128 v[162:165], v0
	ds_read_b128 v[170:173], v191 offset:2048
	ds_read_b128 v[192:195], v191 offset:4096
	ds_read_b128 v[196:199], v191 offset:6144
	ds_read_b128 v[204:207], v0 offset:2048
	ds_read_b128 v[208:211], v0 offset:4096
	ds_read_b128 v[238:241], v0 offset:6144
	v_add_u32_e32 v191, v191, v190
; template <int MI, int NJ> ...
;     ...
;   for (int kt = 0; kt < nk; ++kt) {
;     const int buf = kt & 1;
;     {
;       G8STORE(buf ^ 1);
;       const u16* ga_ = (kt + 2 < nk) ? Ag + (kt + 2) * 64 : Ag + nAoff;
;       const u16* gb_ = (kt + 2 < nk) ? Bg + (kt + 2) * 64 : Bg + nBoff;
;       G8LOADP(ga_, gb_);
;     }
;     __builtin_amdgcn_sched_barrier(0);
;     __builtin_amdgcn_s_setprio(1);
;     const u16* a = ra_ + buf * AROWS * 64;
;     const u16* b = rb_ + buf * BROWS * 64;
; #pragma unroll
;     for (int ks = 0; ks < 2; ++ks) {
;       const u16* a_ = ks ? a + dsw : a;
;       const u16* b_ = ks ? b + dsw : b;
;       bf16x8 bfr[NJ];
; #pragma unroll
;       for (int j = 0; j < NJ; ++j) bfr[j] = *(const bf16x8*)(b_ + j * 16 * 64);
; #pragma unroll
;       for (int ih = 0; ih < MI / 4; ++ih) {
;         bf16x8 af[4];
; #pragma unroll
;         for (int i = 0; i < 4; ++i) af[i] = *(const bf16x8*)(a_ + (ih * 4 + i) * 16 * 64);
; #pragma unroll
;         for (int i = 0; i < 4; ++i)
; #pragma unroll
;           for (int j = 0; j < NJ; ++j) acc[ih * 4 + i][j] = mfma16(af[i], bfr[j], acc[ih * 4 + i][j]);
;       }
;     }
;     __builtin_amdgcn_s_setprio(0);
;     __builtin_amdgcn_sched_barrier(0);
;     __syncthreads();
;   }
.LBB0_481:
	s_setprio 1
	s_waitcnt lgkmcnt(6)
	v_mfma_f32_16x16x32_bf16 v[158:161], v[166:169], v[162:165], v[158:161]
	s_waitcnt lgkmcnt(5)
	v_mfma_f32_16x16x32_bf16 v[154:157], v[170:173], v[162:165], v[154:157]
	s_waitcnt lgkmcnt(4)
	v_mfma_f32_16x16x32_bf16 v[150:153], v[192:195], v[162:165], v[150:153]
	s_waitcnt lgkmcnt(3)
	v_mfma_f32_16x16x32_bf16 v[146:149], v[196:199], v[162:165], v[146:149]
	ds_read_b128 v[162:165], v0 offset:8192
	s_waitcnt lgkmcnt(3)
	v_mfma_f32_16x16x32_bf16 v[142:145], v[166:169], v[204:207], v[142:145]
	v_mfma_f32_16x16x32_bf16 v[138:141], v[170:173], v[204:207], v[138:141]
	v_mfma_f32_16x16x32_bf16 v[134:137], v[192:195], v[204:207], v[134:137]
	v_mfma_f32_16x16x32_bf16 v[130:133], v[196:199], v[204:207], v[130:133]
	ds_read_b128 v[204:207], v0 offset:10240
	s_waitcnt vmcnt(7)
	ds_write_b128 v228, v[10:13]
	global_load_dwordx4 v[10:13], v234, s[50:51]
	s_waitcnt lgkmcnt(4)
	v_mfma_f32_16x16x32_bf16 v[126:129], v[166:169], v[208:211], v[126:129]
	v_mfma_f32_16x16x32_bf16 v[122:125], v[170:173], v[208:211], v[122:125]
	v_mfma_f32_16x16x32_bf16 v[118:121], v[192:195], v[208:211], v[118:121]
	v_mfma_f32_16x16x32_bf16 v[114:117], v[196:199], v[208:211], v[114:117]
	ds_read_b128 v[208:211], v0 offset:12288
	s_waitcnt vmcnt(7)
	ds_write_b128 v228, v[2:5] offset:8192
	global_load_dwordx4 v[2:5], v235, s[50:51]
	ds_read_b128 v[212:215], v191
	ds_read_b128 v[216:219], v191 offset:2048
	s_waitcnt lgkmcnt(7)
	v_mfma_f32_16x16x32_bf16 v[110:113], v[166:169], v[238:241], v[110:113]
	v_mfma_f32_16x16x32_bf16 v[106:109], v[170:173], v[238:241], v[106:109]
	v_mfma_f32_16x16x32_bf16 v[102:105], v[192:195], v[238:241], v[102:105]
	v_mfma_f32_16x16x32_bf16 v[98:101], v[196:199], v[238:241], v[98:101]
	ds_read_b128 v[238:241], v0 offset:14336
	s_waitcnt vmcnt(7)
	ds_write_b128 v228, v[6:9] offset:16384
	global_load_dwordx4 v[6:9], v236, s[50:51]
	ds_read_b128 v[220:223], v191 offset:4096
	ds_read_b128 v[224:227], v191 offset:6144
	s_waitcnt lgkmcnt(10)
	v_mfma_f32_16x16x32_bf16 v[94:97], v[166:169], v[162:165], v[94:97]
	v_mfma_f32_16x16x32_bf16 v[90:93], v[170:173], v[162:165], v[90:93]
	v_mfma_f32_16x16x32_bf16 v[86:89], v[192:195], v[162:165], v[86:89]
	v_mfma_f32_16x16x32_bf16 v[82:85], v[196:199], v[162:165], v[82:85]
	v_add_u32_e32 v0, v0, v190
	ds_read_b128 v[162:165], v0
	s_waitcnt vmcnt(7)
	ds_write_b128 v228, v[14:17] offset:24576
	global_load_dwordx4 v[14:17], v237, s[50:51]
	s_waitcnt lgkmcnt(11)
	v_mfma_f32_16x16x32_bf16 v[78:81], v[166:169], v[204:207], v[78:81]
	v_mfma_f32_16x16x32_bf16 v[70:73], v[170:173], v[204:207], v[70:73]
	v_mfma_f32_16x16x32_bf16 v[66:69], v[192:195], v[204:207], v[66:69]
	v_mfma_f32_16x16x32_bf16 v[58:61], v[196:199], v[204:207], v[58:61]
	ds_read_b128 v[204:207], v0 offset:2048
	s_waitcnt vmcnt(7)
	ds_write_b128 v229, v[18:21]
	global_load_dwordx4 v[18:21], v234, s[52:53]
	s_waitcnt lgkmcnt(11)
	v_mfma_f32_16x16x32_bf16 v[54:57], v[166:169], v[208:211], v[54:57]
	v_mfma_f32_16x16x32_bf16 v[50:53], v[170:173], v[208:211], v[50:53]
	v_mfma_f32_16x16x32_bf16 v[46:49], v[192:195], v[208:211], v[46:49]
	v_mfma_f32_16x16x32_bf16 v[38:41], v[196:199], v[208:211], v[38:41]
	ds_read_b128 v[208:211], v0 offset:4096
	s_waitcnt vmcnt(7)
	ds_write_b128 v229, v[42:45] offset:8192
	global_load_dwordx4 v[42:45], v235, s[52:53]
	s_waitcnt lgkmcnt(9)
	v_mfma_f32_16x16x32_bf16 v[34:37], v[166:169], v[238:241], v[34:37]
	v_mfma_f32_16x16x32_bf16 v[30:33], v[170:173], v[238:241], v[30:33]
	v_mfma_f32_16x16x32_bf16 v[26:29], v[192:195], v[238:241], v[26:29]
	v_mfma_f32_16x16x32_bf16 v[22:25], v[196:199], v[238:241], v[22:25]
	ds_read_b128 v[238:241], v0 offset:6144
	s_waitcnt vmcnt(7)
	ds_write_b128 v229, v[62:65] offset:16384
	global_load_dwordx4 v[62:65], v236, s[52:53]
	s_waitcnt lgkmcnt(7)
	v_mfma_f32_16x16x32_bf16 v[158:161], v[212:215], v[162:165], v[158:161]
	v_mfma_f32_16x16x32_bf16 v[154:157], v[216:219], v[162:165], v[154:157]
	v_mfma_f32_16x16x32_bf16 v[150:153], v[220:223], v[162:165], v[150:153]
	v_mfma_f32_16x16x32_bf16 v[146:149], v[224:227], v[162:165], v[146:149]
	ds_read_b128 v[162:165], v0 offset:8192
	s_waitcnt vmcnt(7)
	ds_write_b128 v229, v[74:77] offset:24576
	global_load_dwordx4 v[74:77], v237, s[52:53]
	s_waitcnt lgkmcnt(7)
	v_mfma_f32_16x16x32_bf16 v[142:145], v[212:215], v[204:207], v[142:145]
	v_mfma_f32_16x16x32_bf16 v[138:141], v[216:219], v[204:207], v[138:141]
	v_mfma_f32_16x16x32_bf16 v[134:137], v[220:223], v[204:207], v[134:137]
	v_mfma_f32_16x16x32_bf16 v[130:133], v[224:227], v[204:207], v[130:133]
	ds_read_b128 v[204:207], v0 offset:10240
	s_waitcnt lgkmcnt(6)
	v_mfma_f32_16x16x32_bf16 v[126:129], v[212:215], v[208:211], v[126:129]
	v_mfma_f32_16x16x32_bf16 v[122:125], v[216:219], v[208:211], v[122:125]
	v_mfma_f32_16x16x32_bf16 v[118:121], v[220:223], v[208:211], v[118:121]
	v_mfma_f32_16x16x32_bf16 v[114:117], v[224:227], v[208:211], v[114:117]
	ds_read_b128 v[208:211], v0 offset:12288
	s_waitcnt lgkmcnt(5)
	v_mfma_f32_16x16x32_bf16 v[110:113], v[212:215], v[238:241], v[110:113]
	v_mfma_f32_16x16x32_bf16 v[106:109], v[216:219], v[238:241], v[106:109]
	v_mfma_f32_16x16x32_bf16 v[102:105], v[220:223], v[238:241], v[102:105]
	v_mfma_f32_16x16x32_bf16 v[98:101], v[224:227], v[238:241], v[98:101]
	ds_read_b128 v[238:241], v0 offset:14336
	s_waitcnt lgkmcnt(4)
	v_mfma_f32_16x16x32_bf16 v[94:97], v[212:215], v[162:165], v[94:97]
	v_mfma_f32_16x16x32_bf16 v[90:93], v[216:219], v[162:165], v[90:93]
	v_mfma_f32_16x16x32_bf16 v[86:89], v[220:223], v[162:165], v[86:89]
	v_mfma_f32_16x16x32_bf16 v[82:85], v[224:227], v[162:165], v[82:85]
	s_waitcnt lgkmcnt(0)
	s_setprio 0
	s_barrier
; template <int MI, int NJ> ...
;     ...
;   for (int kt = 0; kt < nk; ++kt) {
;     const int buf = kt & 1;
;     {
;       G8STORE(buf ^ 1);
;       const u16* ga_ = (kt + 2 < nk) ? Ag + (kt + 2) * 64 : Ag + nAoff;
;       const u16* gb_ = (kt + 2 < nk) ? Bg + (kt + 2) * 64 : Bg + nBoff;
;       G8LOADP(ga_, gb_);
;     }
;     __builtin_amdgcn_sched_barrier(0);
;     __builtin_amdgcn_s_setprio(1);
;     const u16* a = ra_ + buf * AROWS * 64;
;     const u16* b = rb_ + buf * BROWS * 64;
; #pragma unroll
;     for (int ks = 0; ks < 2; ++ks) {
;       const u16* a_ = ks ? a + dsw : a;
;       const u16* b_ = ks ? b + dsw : b;
;       bf16x8 bfr[NJ];
; #pragma unroll
;       for (int j = 0; j < NJ; ++j) bfr[j] = *(const bf16x8*)(b_ + j * 16 * 64);
; #pragma unroll
;       for (int ih = 0; ih < MI / 4; ++ih) {
;         bf16x8 af[4];
; #pragma unroll
;         for (int i = 0; i < 4; ++i) af[i] = *(const bf16x8*)(a_ + (ih * 4 + i) * 16 * 64);
; #pragma unroll
;         for (int i = 0; i < 4; ++i)
; #pragma unroll
;           for (int j = 0; j < NJ; ++j) acc[ih * 4 + i][j] = mfma16(af[i], bfr[j], acc[ih * 4 + i][j]);
;       }
;     }
;     __builtin_amdgcn_s_setprio(0);
;     __builtin_amdgcn_sched_barrier(0);
;     __syncthreads();
;   }
; __device__ __forceinline__ void phase_gemm_f32(const u16* A, const u16* Bt, int K, u16* out, u16* smem,
;                                                volatile LAS unsigned* vb_) {
;     ...
; #pragma unroll
;     for (int i = 0; i < 8; ++i)
; #pragma unroll
;       for (int j = 0; j < 4; ++j)
; #pragma unroll
;         for (int r = 0; r < 4; ++r)
;           smem[(wm * 128 + i * 16 + (lane >> 4) * 4 + r) * 264 + wn * 64 + j * 16 + (lane & 15)] = f2bf(acc[i][j][r]);
;     __syncthreads();
	s_add_i32 s44, s44, 1
	s_add_i32 s39, s39, 64
	s_addk_i32 s43, 0x4000
	s_and_b32 s45, s43, 0x4000
	s_xor_b32 s46, s45, 0x4000
	s_lshl_b32 s46, s46, 1
	v_add_u32_e32 v228, s46, v185
	v_add_u32_e32 v229, s46, v186
	s_add_i32 s46, s44, 2
	s_cmp_lt_u32 s46, s21
	s_cselect_b32 s47, 0, s12
	s_cselect_b32 s46, s39, s13
	s_cselect_b32 s49, 0, s37
	s_cselect_b32 s48, s39, s38
	s_lshl_b64 s[46:47], s[46:47], 1
	s_lshl_b64 s[48:49], s[48:49], 1
	s_add_u32 s50, s62, s46
	s_addc_u32 s51, s63, s47
	s_add_u32 s52, s64, s48
	s_addc_u32 s53, s65, s49
	s_lshl_b32 s45, s45, 1
	v_add_u32_e32 v0, s45, v187
	v_add_u32_e32 v191, s45, v188
	s_setprio 1
	ds_read_b128 v[166:169], v191
	ds_read_b128 v[162:165], v0
	ds_read_b128 v[170:173], v191 offset:2048
	ds_read_b128 v[192:195], v191 offset:4096
	ds_read_b128 v[196:199], v191 offset:6144
	v_mfma_f32_16x16x32_bf16 v[78:81], v[212:215], v[204:207], v[78:81]
	v_mfma_f32_16x16x32_bf16 v[70:73], v[216:219], v[204:207], v[70:73]
	v_mfma_f32_16x16x32_bf16 v[66:69], v[220:223], v[204:207], v[66:69]
	v_mfma_f32_16x16x32_bf16 v[58:61], v[224:227], v[204:207], v[58:61]
	ds_read_b128 v[204:207], v0 offset:2048
	v_mfma_f32_16x16x32_bf16 v[54:57], v[212:215], v[208:211], v[54:57]
	v_mfma_f32_16x16x32_bf16 v[50:53], v[216:219], v[208:211], v[50:53]
	v_mfma_f32_16x16x32_bf16 v[46:49], v[220:223], v[208:211], v[46:49]
	v_mfma_f32_16x16x32_bf16 v[38:41], v[224:227], v[208:211], v[38:41]
	ds_read_b128 v[208:211], v0 offset:4096
	v_mfma_f32_16x16x32_bf16 v[34:37], v[212:215], v[238:241], v[34:37]
	v_mfma_f32_16x16x32_bf16 v[30:33], v[216:219], v[238:241], v[30:33]
	v_mfma_f32_16x16x32_bf16 v[26:29], v[220:223], v[238:241], v[26:29]
	v_mfma_f32_16x16x32_bf16 v[22:25], v[224:227], v[238:241], v[22:25]
	ds_read_b128 v[238:241], v0 offset:6144
	v_add_u32_e32 v191, v191, v190
	s_setprio 0
	s_cmp_lg_u32 s21, s44
	s_cbranch_scc1 .LBB0_481
	v_and_b32_e32 v228, 15, v175
	v_bfe_u32 v229, v175, 8, 1
	v_lshl_or_b32 v228, v229, 7, v228
	v_mul_u32_u24_e32 v228, 0x210, v228
	v_bfe_u32 v229, v175, 6, 2
	v_lshl_add_u32 v228, v229, 7, v228
	v_bfe_u32 v229, v175, 4, 2
	v_lshl_add_u32 v228, v229, 3, v228
	v_cvt_pk_bf16_f32 v158, v158, v159
	v_cvt_pk_bf16_f32 v159, v160, v161
	v_cvt_pk_bf16_f32 v154, v154, v155
	v_cvt_pk_bf16_f32 v155, v156, v157
	v_cvt_pk_bf16_f32 v150, v150, v151
	v_cvt_pk_bf16_f32 v151, v152, v153
	v_cvt_pk_bf16_f32 v146, v146, v147
	v_cvt_pk_bf16_f32 v147, v148, v149
	ds_write_b64 v228, v[158:159]
	ds_write_b64 v228, v[154:155] offset:32
	ds_write_b64 v228, v[150:151] offset:64
	ds_write_b64 v228, v[146:147] offset:96
	v_cvt_pk_bf16_f32 v142, v142, v143
	v_cvt_pk_bf16_f32 v143, v144, v145
	v_cvt_pk_bf16_f32 v138, v138, v139
	v_cvt_pk_bf16_f32 v139, v140, v141
	v_cvt_pk_bf16_f32 v134, v134, v135
	v_cvt_pk_bf16_f32 v135, v136, v137
	v_cvt_pk_bf16_f32 v130, v130, v131
	v_cvt_pk_bf16_f32 v131, v132, v133
	ds_write_b64 v228, v[142:143] offset:8448
	ds_write_b64 v228, v[138:139] offset:8480
	ds_write_b64 v228, v[134:135] offset:8512
	ds_write_b64 v228, v[130:131] offset:8544
	v_cvt_pk_bf16_f32 v126, v126, v127
	v_cvt_pk_bf16_f32 v127, v128, v129
	v_cvt_pk_bf16_f32 v122, v122, v123
	v_cvt_pk_bf16_f32 v123, v124, v125
	v_cvt_pk_bf16_f32 v118, v118, v119
	v_cvt_pk_bf16_f32 v119, v120, v121
	v_cvt_pk_bf16_f32 v114, v114, v115
	v_cvt_pk_bf16_f32 v115, v116, v117
	ds_write_b64 v228, v[126:127] offset:16896
	ds_write_b64 v228, v[122:123] offset:16928
	ds_write_b64 v228, v[118:119] offset:16960
	ds_write_b64 v228, v[114:115] offset:16992
	v_cvt_pk_bf16_f32 v110, v110, v111
	v_cvt_pk_bf16_f32 v111, v112, v113
	v_cvt_pk_bf16_f32 v106, v106, v107
	v_cvt_pk_bf16_f32 v107, v108, v109
	v_cvt_pk_bf16_f32 v102, v102, v103
	v_cvt_pk_bf16_f32 v103, v104, v105
	v_cvt_pk_bf16_f32 v98, v98, v99
	v_cvt_pk_bf16_f32 v99, v100, v101
	ds_write_b64 v228, v[110:111] offset:25344
	ds_write_b64 v228, v[106:107] offset:25376
	ds_write_b64 v228, v[102:103] offset:25408
	ds_write_b64 v228, v[98:99] offset:25440
	v_cvt_pk_bf16_f32 v94, v94, v95
	v_cvt_pk_bf16_f32 v95, v96, v97
	v_cvt_pk_bf16_f32 v90, v90, v91
	v_cvt_pk_bf16_f32 v91, v92, v93
	v_cvt_pk_bf16_f32 v86, v86, v87
	v_cvt_pk_bf16_f32 v87, v88, v89
	v_cvt_pk_bf16_f32 v82, v82, v83
	v_cvt_pk_bf16_f32 v83, v84, v85
	ds_write_b64 v228, v[94:95] offset:33792
	ds_write_b64 v228, v[90:91] offset:33824
	ds_write_b64 v228, v[86:87] offset:33856
	ds_write_b64 v228, v[82:83] offset:33888
	v_cvt_pk_bf16_f32 v78, v78, v79
	v_cvt_pk_bf16_f32 v79, v80, v81
	v_cvt_pk_bf16_f32 v70, v70, v71
	v_cvt_pk_bf16_f32 v71, v72, v73
	v_cvt_pk_bf16_f32 v66, v66, v67
	v_cvt_pk_bf16_f32 v67, v68, v69
	v_cvt_pk_bf16_f32 v58, v58, v59
	v_cvt_pk_bf16_f32 v59, v60, v61
	ds_write_b64 v228, v[78:79] offset:42240
	ds_write_b64 v228, v[70:71] offset:42272
	ds_write_b64 v228, v[66:67] offset:42304
	ds_write_b64 v228, v[58:59] offset:42336
	v_cvt_pk_bf16_f32 v54, v54, v55
	v_cvt_pk_bf16_f32 v55, v56, v57
	v_cvt_pk_bf16_f32 v50, v50, v51
	v_cvt_pk_bf16_f32 v51, v52, v53
	v_cvt_pk_bf16_f32 v46, v46, v47
	v_cvt_pk_bf16_f32 v47, v48, v49
	v_cvt_pk_bf16_f32 v38, v38, v39
	v_cvt_pk_bf16_f32 v39, v40, v41
	ds_write_b64 v228, v[54:55] offset:50688
	ds_write_b64 v228, v[50:51] offset:50720
	ds_write_b64 v228, v[46:47] offset:50752
	ds_write_b64 v228, v[38:39] offset:50784
	v_cvt_pk_bf16_f32 v34, v34, v35
	v_cvt_pk_bf16_f32 v35, v36, v37
	v_cvt_pk_bf16_f32 v30, v30, v31
	v_cvt_pk_bf16_f32 v31, v32, v33
	v_cvt_pk_bf16_f32 v26, v26, v27
	v_cvt_pk_bf16_f32 v27, v28, v29
	v_cvt_pk_bf16_f32 v22, v22, v23
	v_cvt_pk_bf16_f32 v23, v24, v25
	ds_write_b64 v228, v[34:35] offset:59136
	ds_write_b64 v228, v[30:31] offset:59168
	ds_write_b64 v228, v[26:27] offset:59200
	ds_write_b64 v228, v[22:23] offset:59232
	s_ashr_i32 s43, s42, 31
	v_mov_b32_e32 v34, v175
	s_lshl_b64 s[12:13], s[42:43], 1
	s_waitcnt lgkmcnt(0)
	s_barrier
; #define RTID opaque_tid()
; __device__ __forceinline__ void phase_gemm_f32(const u16* A, const u16* Bt, int K, u16* out, u16* smem,
;                                                volatile LAS unsigned* vb_) {
;     ...
;     const int tid2 = RTID;
; #pragma unroll
;     for (int k = 0; k < 16; ++k) {
;       const int c = tid2 + 512 * k;
;       const int row = c >> 5, ch = c & 31;
;       const uint4 v = *(const uint4*)(smem + row * 264 + ch * 8);
;       *(uint4*)(out + (size_t)(mt * 256 + row) * 1024 + nt * 256 + ch * 8) = v;
;     }
;     __syncthreads();
	s_add_u32 s12, s11, s12
	v_lshlrev_b32_e32 v0, 4, v34
	v_and_b32_e32 v0, 0x1f0, v0
	s_addc_u32 s13, s20, s13
	v_ashrrev_i32_e32 v26, 5, v34
	v_lshl_add_u64 v[30:31], s[12:13], 0, v[0:1]
	v_mad_u64_u32 v[22:23], s[12:13], v26, s2, v[0:1]
	v_add_u32_e32 v26, s23, v26
	v_ashrrev_i32_e32 v27, 31, v26
	ds_read_b128 v[22:25], v22
	v_lshlrev_b64 v[26:27], 11, v[26:27]
	v_lshl_add_u64 v[32:33], v[30:31], 0, v[26:27]
	v_add_u32_e32 v26, 0x200, v34
	v_ashrrev_i32_e32 v35, 5, v26
	v_mad_u64_u32 v[26:27], s[12:13], v35, s2, v[0:1]
	ds_read_b128 v[26:29], v26
	s_waitcnt lgkmcnt(1)
	global_store_dwordx4 v[32:33], v[22:25], off
	s_and_b64 vcc, exec, s[40:41]
	s_mov_b32 s37, s36
	v_add_u32_e32 v22, s23, v35
	v_ashrrev_i32_e32 v23, 31, v22
	v_lshlrev_b64 v[22:23], 11, v[22:23]
	v_lshl_add_u64 v[22:23], v[30:31], 0, v[22:23]
	s_waitcnt lgkmcnt(0)
	global_store_dwordx4 v[22:23], v[26:29], off
	v_add_u32_e32 v22, 0x400, v34
	s_nop 0
	v_ashrrev_i32_e32 v26, 5, v22
	v_mad_u64_u32 v[22:23], s[12:13], v26, s2, v[0:1]
	v_add_u32_e32 v26, s23, v26
	v_ashrrev_i32_e32 v27, 31, v26
	ds_read_b128 v[22:25], v22
	v_lshlrev_b64 v[26:27], 11, v[26:27]
	v_lshl_add_u64 v[32:33], v[30:31], 0, v[26:27]
	v_add_u32_e32 v26, 0x600, v34
	v_ashrrev_i32_e32 v35, 5, v26
	v_mad_u64_u32 v[26:27], s[12:13], v35, s2, v[0:1]
	ds_read_b128 v[26:29], v26
	s_waitcnt lgkmcnt(1)
	global_store_dwordx4 v[32:33], v[22:25], off
	s_nop 1
	v_add_u32_e32 v22, s23, v35
	v_ashrrev_i32_e32 v23, 31, v22
	v_lshlrev_b64 v[22:23], 11, v[22:23]
	v_lshl_add_u64 v[22:23], v[30:31], 0, v[22:23]
	s_waitcnt lgkmcnt(0)
	global_store_dwordx4 v[22:23], v[26:29], off
	v_add_u32_e32 v22, 0x800, v34
	s_nop 0
	v_ashrrev_i32_e32 v26, 5, v22
	v_mad_u64_u32 v[22:23], s[12:13], v26, s2, v[0:1]
	v_add_u32_e32 v26, s23, v26
	v_ashrrev_i32_e32 v27, 31, v26
	ds_read_b128 v[22:25], v22
	v_lshlrev_b64 v[26:27], 11, v[26:27]
	v_lshl_add_u64 v[32:33], v[30:31], 0, v[26:27]
	v_add_u32_e32 v26, 0xa00, v34
	v_ashrrev_i32_e32 v35, 5, v26
	v_mad_u64_u32 v[26:27], s[12:13], v35, s2, v[0:1]
	ds_read_b128 v[26:29], v26
	s_waitcnt lgkmcnt(1)
	global_store_dwordx4 v[32:33], v[22:25], off
	s_nop 1
	v_add_u32_e32 v22, s23, v35
	v_ashrrev_i32_e32 v23, 31, v22
	v_lshlrev_b64 v[22:23], 11, v[22:23]
	v_lshl_add_u64 v[22:23], v[30:31], 0, v[22:23]
	s_waitcnt lgkmcnt(0)
	global_store_dwordx4 v[22:23], v[26:29], off
	v_add_u32_e32 v22, 0xc00, v34
	s_nop 0
	v_ashrrev_i32_e32 v26, 5, v22
	v_mad_u64_u32 v[22:23], s[12:13], v26, s2, v[0:1]
	v_add_u32_e32 v26, s23, v26
	v_ashrrev_i32_e32 v27, 31, v26
	ds_read_b128 v[22:25], v22
	v_lshlrev_b64 v[26:27], 11, v[26:27]
	v_lshl_add_u64 v[32:33], v[30:31], 0, v[26:27]
	v_add_u32_e32 v26, 0xe00, v34
	v_ashrrev_i32_e32 v35, 5, v26
	v_mad_u64_u32 v[26:27], s[12:13], v35, s2, v[0:1]
	ds_read_b128 v[26:29], v26
	s_waitcnt lgkmcnt(1)
	global_store_dwordx4 v[32:33], v[22:25], off
	s_nop 1
	v_add_u32_e32 v22, s23, v35
	v_ashrrev_i32_e32 v23, 31, v22
	v_lshlrev_b64 v[22:23], 11, v[22:23]
	v_lshl_add_u64 v[22:23], v[30:31], 0, v[22:23]
	s_waitcnt lgkmcnt(0)
	global_store_dwordx4 v[22:23], v[26:29], off
	v_add_u32_e32 v22, 0x1000, v34
	s_nop 0
	v_ashrrev_i32_e32 v26, 5, v22
	v_mad_u64_u32 v[22:23], s[12:13], v26, s2, v[0:1]
	v_add_u32_e32 v26, s23, v26
	v_ashrrev_i32_e32 v27, 31, v26
	ds_read_b128 v[22:25], v22
	v_lshlrev_b64 v[26:27], 11, v[26:27]
	v_lshl_add_u64 v[32:33], v[30:31], 0, v[26:27]
	v_add_u32_e32 v26, 0x1200, v34
	v_ashrrev_i32_e32 v35, 5, v26
	v_mad_u64_u32 v[26:27], s[12:13], v35, s2, v[0:1]
	ds_read_b128 v[26:29], v26
	s_waitcnt lgkmcnt(1)
	global_store_dwordx4 v[32:33], v[22:25], off
	s_nop 1
	v_add_u32_e32 v22, s23, v35
	v_ashrrev_i32_e32 v23, 31, v22
	v_lshlrev_b64 v[22:23], 11, v[22:23]
	v_lshl_add_u64 v[22:23], v[30:31], 0, v[22:23]
	s_waitcnt lgkmcnt(0)
	global_store_dwordx4 v[22:23], v[26:29], off
	v_add_u32_e32 v22, 0x1400, v34
	s_nop 0
	v_ashrrev_i32_e32 v26, 5, v22
	v_mad_u64_u32 v[22:23], s[12:13], v26, s2, v[0:1]
	v_add_u32_e32 v26, s23, v26
	v_ashrrev_i32_e32 v27, 31, v26
	ds_read_b128 v[22:25], v22
	v_lshlrev_b64 v[26:27], 11, v[26:27]
	v_lshl_add_u64 v[32:33], v[30:31], 0, v[26:27]
	v_add_u32_e32 v26, 0x1600, v34
	v_ashrrev_i32_e32 v35, 5, v26
	v_mad_u64_u32 v[26:27], s[12:13], v35, s2, v[0:1]
	ds_read_b128 v[26:29], v26
	s_waitcnt lgkmcnt(1)
	global_store_dwordx4 v[32:33], v[22:25], off
	s_nop 1
	v_add_u32_e32 v22, s23, v35
	v_ashrrev_i32_e32 v23, 31, v22
	v_lshlrev_b64 v[22:23], 11, v[22:23]
	v_lshl_add_u64 v[22:23], v[30:31], 0, v[22:23]
	s_waitcnt lgkmcnt(0)
	global_store_dwordx4 v[22:23], v[26:29], off
	v_add_u32_e32 v22, 0x1800, v34
	s_nop 0
	v_ashrrev_i32_e32 v26, 5, v22
	v_mad_u64_u32 v[22:23], s[12:13], v26, s2, v[0:1]
	v_add_u32_e32 v26, s23, v26
	v_ashrrev_i32_e32 v27, 31, v26
	ds_read_b128 v[22:25], v22
	v_lshlrev_b64 v[26:27], 11, v[26:27]
	v_lshl_add_u64 v[32:33], v[30:31], 0, v[26:27]
	v_add_u32_e32 v26, 0x1a00, v34
	v_ashrrev_i32_e32 v35, 5, v26
	v_mad_u64_u32 v[26:27], s[12:13], v35, s2, v[0:1]
	ds_read_b128 v[26:29], v26
	s_waitcnt lgkmcnt(1)
	global_store_dwordx4 v[32:33], v[22:25], off
	s_nop 1
	v_add_u32_e32 v22, s23, v35
	v_ashrrev_i32_e32 v23, 31, v22
	v_lshlrev_b64 v[22:23], 11, v[22:23]
	v_lshl_add_u64 v[22:23], v[30:31], 0, v[22:23]
	s_waitcnt lgkmcnt(0)
	global_store_dwordx4 v[22:23], v[26:29], off
	v_add_u32_e32 v22, 0x1c00, v34
	s_nop 0
	v_ashrrev_i32_e32 v26, 5, v22
	v_mad_u64_u32 v[22:23], s[12:13], v26, s2, v[0:1]
	v_add_u32_e32 v26, s23, v26
	v_ashrrev_i32_e32 v27, 31, v26
	ds_read_b128 v[22:25], v22
	v_lshlrev_b64 v[26:27], 11, v[26:27]
	v_lshl_add_u64 v[32:33], v[30:31], 0, v[26:27]
	v_add_u32_e32 v26, 0x1e00, v34
	v_ashrrev_i32_e32 v34, 5, v26
	v_mad_u64_u32 v[26:27], s[12:13], v34, s2, v[0:1]
	ds_read_b128 v[26:29], v26
	s_waitcnt lgkmcnt(1)
	global_store_dwordx4 v[32:33], v[22:25], off
	s_mov_b64 s[12:13], -1
	s_nop 0
	v_add_u32_e32 v22, s23, v34
	v_ashrrev_i32_e32 v23, 31, v22
	v_lshlrev_b64 v[22:23], 11, v[22:23]
	v_lshl_add_u64 v[22:23], v[30:31], 0, v[22:23]
	s_waitcnt lgkmcnt(0)
	global_store_dwordx4 v[22:23], v[26:29], off
	s_barrier
	s_cbranch_vccz .LBB0_478

; #define ZERO_ACC8(acc, NJ_)                             \
;   _Pragma("unroll") for (int i_ = 0; i_ < 8; ++i_)      \
;   _Pragma("unroll") for (int j_ = 0; j_ < (NJ_); ++j_) { acc[i_][j_] = (f32x4){0.f, 0.f, 0.f, 0.f}; }
; template <int MI, int NJ> ...
;     ...
;   const int lrow = tid >> 3, lkc = tid & 7;
;   const u16* Ag = A + (size_t)(row0 + lrow) * lda + kbeg + lkc * 8;
;   const u16* Bg = Bt + (size_t)(col0 + lrow) * ldb + kbeg + lkc * 8;
;   const size_t a64 = (size_t)64 * lda, b64 = (size_t)64 * ldb;
;   const int nk = (kend - kbeg) >> 6;
;   const long long nAoff = (long long)(nrow0 - row0) * lda + (nkbeg - kbeg);
;   const long long nBoff = (long long)(ncol0 - col0) * ldb + (nkbeg - kbeg);
;   u16* wa = sA + lrow * 64 + ((lkc ^ (lrow & 7)) * 8);
;   u16* wb = sB + lrow * 64 + ((lkc ^ (lrow & 7)) * 8);
;     ...
;   if (!pre) G8LOADP(Ag, Bg);
;   G8STORE(0);
;   {
;     const u16* ga_ = (1 < nk) ? Ag + 64 : Ag + nAoff;
;     const u16* gb_ = (1 < nk) ? Bg + 64 : Bg + nBoff;
;     G8LOADP(ga_, gb_);
;   }
;   __syncthreads();
;   const int sw0 = ((lane >> 4) ^ (lane & 7)) * 8;
;   const int dsw = (sw0 ^ 32) - sw0;
;   const u16* ra_ = sA + (wm * (16 * MI) + (lane & 15)) * 64 + sw0;
;   const u16* rb_ = sB + (wn * (16 * NJ) + (lane & 15)) * 64 + sw0;
; __device__ __forceinline__ void phase_ffn_up(const Params& p, const u16* Wgu, u16* smem, volatile LAS unsigned* vb_) {
;     ...
;   for (int lt = vb >> 3; lt < 8 * 20; lt += step) {
;     const int nt = lt >> 3, mt = (vb & 7) * 8 + (lt & 7);
;     const int ltn = (lt + step < 8 * 20) ? lt + step : lt;
;     f32x4 acc[8][4];
;     ZERO_ACC8(acc, 4);
;     gemm8<8, 4>(acc, G8REGS_ARGS, pre, H, 1024, Wgu, 1024, 0, 1024, mt * 256, nt * 256,
;                 ((vb & 7) * 8 + (ltn & 7)) * 256, (ltn >> 3) * 256, 0, smem, tid);
.LBB0_595:
	s_nop 0
	v_readlane_b32 s0, v255, 0
	v_readlane_b32 s1, v255, 1
	s_and_b64 vcc, exec, s[0:1]
	s_cbranch_vccz .LBB0_608
	s_waitcnt vmcnt(15)
	v_mov_b32_e32 v2, v175
	ds_read_b32 v0, v230
	s_cmp_eq_u32 s82, 0
	s_cselect_b32 s0, 0, 0x1080000
	s_add_u32 s0, s72, s0
	s_addc_u32 s1, s73, 0
	s_waitcnt lgkmcnt(0)
	v_readfirstlane_b32 s37, v0
	s_ashr_i32 s36, s37, 3
	v_ashrrev_i32_e32 v176, 3, v2
	v_lshlrev_b32_e32 v3, 4, v2
	v_lshrrev_b32_e32 v4, 4, v2
	v_and_b32_e32 v5, 7, v2
	v_lshrrev_b32_e32 v180, 1, v2
	v_and_b32_e32 v179, 15, v2
	s_waitcnt vmcnt(13)
	v_lshrrev_b32_e32 v6, 2, v2
	s_mov_b32 s10, 0x1ffff80
	v_ashrrev_i32_e32 v177, 8, v2
	v_bfe_u32 v178, v2, 6, 2
	s_cmpk_gt_i32 s36, 0x9f
	v_and_b32_e32 v0, 0x70, v3
	v_xor_b32_e32 v184, v176, v2
	v_bitop3_b32 v182, v4, v5, 3 bitop3:0x6c
	v_and_or_b32 v183, v180, s10, v179
	v_and_b32_e32 v181, 12, v6
	s_cbranch_scc1 .LBB0_603
	v_lshlrev_b32_e32 v4, 4, v184
	s_lshl_b32 s10, s37, 3
	v_and_b32_e32 v4, 0x70, v4
	s_and_b32 s38, s10, 56
	v_readlane_b32 s10, v252, 38
	v_lshl_or_b32 v185, v176, 7, v4
	v_lshlrev_b32_e32 v4, 3, v182
	v_readlane_b32 s11, v252, 39
	v_xor_b32_e32 v5, 32, v4
	v_lshlrev_b32_e32 v6, 7, v2
	v_lshl_add_u64 v[162:163], s[10:11], 0, v[0:1]
	v_sub_u32_e32 v5, v5, v4
	v_lshlrev_b32_e32 v4, 4, v182
	v_and_b32_e32 v6, 0x6780, v6
	s_mov_b32 s10, 0x10000
	v_lshl_or_b32 v187, v183, 7, v4
	v_or3_b32 v188, v6, v4, s10
	v_lshlrev_b32_e32 v4, 1, v179
	v_lshl_or_b32 v8, v177, 7, v181
	v_lshl_or_b32 v4, v178, 6, v4
	v_and_b32_e32 v6, 0xf0, v3
	v_mov_b32_e32 v7, v1
	s_movk_i32 s12, 0x110
	v_lshl_add_u64 v[166:167], s[78:79], 0, v[6:7]
	v_ashrrev_i32_e32 v189, 4, v2
	v_mad_u64_u32 v[168:169], s[10:11], v8, s12, v[4:5]
	v_add_u32_e32 v4, 0x200, v2
	v_add_u32_e32 v7, 0x400, v2
	v_add_u32_e32 v8, 0x600, v2
	v_add_u32_e32 v9, 0x800, v2
	s_waitcnt vmcnt(12)
	v_add_u32_e32 v10, 0xa00, v2
	v_add_u32_e32 v11, 0xc00, v2
	v_add_u32_e32 v2, 0xe00, v2
	v_ashrrev_i32_e32 v169, 4, v4
	v_ashrrev_i32_e32 v190, 4, v7
	v_ashrrev_i32_e32 v191, 4, v8
	v_ashrrev_i32_e32 v192, 4, v9
	v_ashrrev_i32_e32 v193, 4, v10
	v_ashrrev_i32_e32 v194, 4, v11
	v_ashrrev_i32_e32 v195, 4, v2
	v_mul_lo_u32 v3, v189, s12
	v_mul_lo_u32 v4, v169, s12
	v_mul_lo_u32 v7, v190, s12
	v_mul_lo_u32 v8, v191, s12
	v_mul_lo_u32 v9, v192, s12
	v_mul_lo_u32 v10, v193, s12
	v_mul_lo_u32 v11, v194, s12
	v_mul_lo_u32 v2, v195, s12
	v_lshl_add_u64 v[164:165], s[0:1], 0, v[0:1]
	v_add_u32_e32 v186, 0x10000, v185
	s_mov_b64 s[12:13], 0
	v_lshlrev_b32_e32 v196, 1, v5
	v_add_u32_e32 v197, v6, v3
	v_add_u32_e32 v198, v6, v4
	v_add_u32_e32 v199, v6, v7
	v_add_u32_e32 v200, v6, v8
	v_add_u32_e32 v204, v6, v9
	v_add_u32_e32 v205, v6, v10
	v_add_u32_e32 v206, v6, v11
	v_add_u32_e32 v207, v6, v2
	s_mov_b32 s20, s36
	v_bfe_u32 v169, v175, 3, 3
	v_and_b32_e32 v194, 7, v175
	v_lshlrev_b32_e32 v194, 4, v194
	v_lshl_add_u32 v169, v169, 11, v194
	v_add_u32_e32 v194, 0x20000, v169
	v_add_u32_e32 v195, 0x40000, v169
	v_add_u32_e32 v198, 0x60000, v169
.LBB0_598:
	s_and_b32 s22, s20, 7
	s_or_b32 s10, s22, s38
	s_lshl_b32 s39, s10, 8
	s_waitcnt vmcnt(4)
	v_add_u32_e32 v34, s39, v176
	s_ashr_i32 s40, s20, 3
	v_ashrrev_i32_e32 v35, 31, v34
	s_lshl_b32 s21, s40, 8
	v_lshlrev_b64 v[34:35], 11, v[34:35]
	v_lshl_add_u64 v[170:171], v[162:163], 0, v[34:35]
	v_add_u32_e32 v34, s21, v176
	v_ashrrev_i32_e32 v35, 31, v34
	v_lshlrev_b64 v[34:35], 11, v[34:35]
	v_lshl_add_u64 v[172:173], v[164:165], 0, v[34:35]
	v_readfirstlane_b32 s62, v170
	v_readfirstlane_b32 s63, v171
	v_readfirstlane_b32 s64, v172
	v_readfirstlane_b32 s65, v173
	s_nop 3
	s_and_b64 vcc, exec, s[12:13]
	s_cbranch_vccnz .LBB0_600
	global_load_dwordx4 v[2:5], v169, s[62:63]
	global_load_dwordx4 v[6:9], v194, s[62:63]
	global_load_dwordx4 v[10:13], v195, s[62:63]
	global_load_dwordx4 v[18:21], v198, s[62:63]
	global_load_dwordx4 v[14:17], v169, s[64:65]
	global_load_dwordx4 v[22:25], v194, s[64:65]
	global_load_dwordx4 v[26:29], v195, s[64:65]
	global_load_dwordx4 v[30:33], v198, s[64:65]
.LBB0_600:
	s_waitcnt vmcnt(5)
	ds_write_b128 v185, v[2:5]
	ds_write_b128 v185, v[6:9] offset:8192
	ds_write_b128 v185, v[10:13] offset:16384
	s_waitcnt vmcnt(3)
	ds_write_b128 v185, v[18:21] offset:24576
	ds_write_b128 v186, v[14:17]
	s_waitcnt vmcnt(2)
	ds_write_b128 v186, v[22:25] offset:8192
	s_waitcnt vmcnt(1)
	ds_write_b128 v186, v[26:29] offset:16384
	s_waitcnt vmcnt(0)
; template <int MI, int NJ> ...
;     ...
;   if (!pre) G8LOADP(Ag, Bg);
;   G8STORE(0);
;   {
;     const u16* ga_ = (1 < nk) ? Ag + 64 : Ag + nAoff;
;     const u16* gb_ = (1 < nk) ? Bg + 64 : Bg + nBoff;
;     G8LOADP(ga_, gb_);
;   }
;   __syncthreads();
;   const int sw0 = ((lane >> 4) ^ (lane & 7)) * 8;
;   const int dsw = (sw0 ^ 32) - sw0;
;   const u16* ra_ = sA + (wm * (16 * MI) + (lane & 15)) * 64 + sw0;
;   const u16* rb_ = sB + (wn * (16 * NJ) + (lane & 15)) * 64 + sw0;
;   for (int kt = 0; kt < nk; ++kt) {
;     const int buf = kt & 1;
;     {
;       G8STORE(buf ^ 1);
;       const u16* ga_ = (kt + 2 < nk) ? Ag + (kt + 2) * 64 : Ag + nAoff;
;       const u16* gb_ = (kt + 2 < nk) ? Bg + (kt + 2) * 64 : Bg + nBoff;
;       G8LOADP(ga_, gb_);
;     }
;     __builtin_amdgcn_sched_barrier(0);
;     __builtin_amdgcn_s_setprio(1);
;     const u16* a = ra_ + buf * AROWS * 64;
;     const u16* b = rb_ + buf * BROWS * 64;
; #pragma unroll
;     for (int ks = 0; ks < 2; ++ks) {
;       const u16* a_ = ks ? a + dsw : a;
;       const u16* b_ = ks ? b + dsw : b;
;       bf16x8 bfr[NJ];
; #pragma unroll
;       for (int j = 0; j < NJ; ++j) bfr[j] = *(const bf16x8*)(b_ + j * 16 * 64);
	ds_write_b128 v186, v[30:33] offset:24576
	s_add_i32 s41, s20, s70
	s_cmpk_gt_i32 s41, 0x9f
	s_cselect_b64 s[10:11], -1, 0
	global_load_dwordx4 v[2:5], v169, s[62:63] offset:128
	global_load_dwordx4 v[6:9], v194, s[62:63] offset:128
	global_load_dwordx4 v[10:13], v195, s[62:63] offset:128
	global_load_dwordx4 v[18:21], v198, s[62:63] offset:128
	global_load_dwordx4 v[14:17], v169, s[64:65] offset:128
	global_load_dwordx4 v[22:25], v194, s[64:65] offset:128
	global_load_dwordx4 v[26:29], v195, s[64:65] offset:128
	global_load_dwordx4 v[30:33], v198, s[64:65] offset:128
	s_cmpk_lt_i32 s41, 0xa0
	s_cselect_b32 s12, s41, s20
	s_and_b32 s13, s12, 7
	s_lshl_b32 s12, s12, 5
	s_and_b32 s20, s12, 0xffffff00
	s_sub_i32 s12, s13, s22
	s_lshl_b32 s12, s12, 8
	s_sub_i32 s20, s20, s21
	s_ashr_i32 s13, s12, 31
	s_ashr_i32 s21, s20, 31
	v_mov_b32_e32 v34, 0
	s_lshl_b64 s[12:13], s[12:13], 10
	s_lshl_b64 s[20:21], s[20:21], 10
	s_mov_b32 s42, 0
	s_mov_b64 s[22:23], 0x80
	s_mov_b32 s43, 0
	v_mov_b32_e32 v35, v34
	v_mov_b32_e32 v36, v34
	v_mov_b32_e32 v37, v34
	v_mov_b32_e32 v38, v34
	v_mov_b32_e32 v39, v34
	v_mov_b32_e32 v40, v34
	v_mov_b32_e32 v41, v34
	v_mov_b32_e32 v42, v34
	v_mov_b32_e32 v43, v34
	v_mov_b32_e32 v44, v34
	v_mov_b32_e32 v45, v34
	v_mov_b32_e32 v46, v34
	v_mov_b32_e32 v47, v34
	v_mov_b32_e32 v48, v34
	v_mov_b32_e32 v49, v34
	v_mov_b32_e32 v50, v34
	v_mov_b32_e32 v51, v34
	v_mov_b32_e32 v52, v34
	v_mov_b32_e32 v53, v34
	v_mov_b32_e32 v54, v34
	v_mov_b32_e32 v55, v34
	v_mov_b32_e32 v56, v34
	v_mov_b32_e32 v57, v34
	v_mov_b32_e32 v58, v34
	v_mov_b32_e32 v59, v34
	v_mov_b32_e32 v60, v34
	v_mov_b32_e32 v61, v34
	v_mov_b32_e32 v62, v34
	v_mov_b32_e32 v63, v34
	v_mov_b32_e32 v64, v34
	v_mov_b32_e32 v65, v34
	v_mov_b32_e32 v66, v34
	v_mov_b32_e32 v67, v34
	v_mov_b32_e32 v68, v34
	v_mov_b32_e32 v69, v34
	v_mov_b32_e32 v70, v34
	v_mov_b32_e32 v71, v34
	v_mov_b32_e32 v72, v34
	v_mov_b32_e32 v73, v34
	v_mov_b32_e32 v74, v34
	v_mov_b32_e32 v75, v34
	v_mov_b32_e32 v76, v34
	v_mov_b32_e32 v77, v34
	v_mov_b32_e32 v78, v34
	v_mov_b32_e32 v79, v34
	v_mov_b32_e32 v80, v34
	v_mov_b32_e32 v81, v34
	v_mov_b32_e32 v82, v34
	v_mov_b32_e32 v83, v34
	v_mov_b32_e32 v84, v34
	v_mov_b32_e32 v85, v34
	v_mov_b32_e32 v86, v34
	v_mov_b32_e32 v87, v34
	v_mov_b32_e32 v88, v34
	v_mov_b32_e32 v89, v34
	v_mov_b32_e32 v90, v34
	v_mov_b32_e32 v91, v34
	v_mov_b32_e32 v92, v34
	v_mov_b32_e32 v93, v34
	v_mov_b32_e32 v94, v34
	v_mov_b32_e32 v95, v34
	v_mov_b32_e32 v96, v34
	v_mov_b32_e32 v97, v34
	v_mov_b32_e32 v98, v34
	v_mov_b32_e32 v99, v34
	v_mov_b32_e32 v100, v34
	v_mov_b32_e32 v101, v34
	v_mov_b32_e32 v102, v34
	v_mov_b32_e32 v103, v34
	v_mov_b32_e32 v104, v34
	v_mov_b32_e32 v105, v34
	v_mov_b32_e32 v106, v34
	v_mov_b32_e32 v107, v34
	v_mov_b32_e32 v108, v34
	v_mov_b32_e32 v109, v34
	v_mov_b32_e32 v110, v34
	v_mov_b32_e32 v111, v34
	v_mov_b32_e32 v112, v34
	v_mov_b32_e32 v113, v34
	v_mov_b32_e32 v114, v34
	v_mov_b32_e32 v115, v34
	v_mov_b32_e32 v116, v34
	v_mov_b32_e32 v117, v34
	v_mov_b32_e32 v118, v34
	v_mov_b32_e32 v119, v34
	v_mov_b32_e32 v120, v34
	v_mov_b32_e32 v121, v34
	v_mov_b32_e32 v122, v34
	v_mov_b32_e32 v123, v34
	v_mov_b32_e32 v124, v34
	v_mov_b32_e32 v125, v34
	v_mov_b32_e32 v126, v34
	v_mov_b32_e32 v127, v34
	v_mov_b32_e32 v128, v34
	v_mov_b32_e32 v129, v34
	v_mov_b32_e32 v130, v34
	v_mov_b32_e32 v131, v34
	v_mov_b32_e32 v132, v34
	v_mov_b32_e32 v133, v34
	v_mov_b32_e32 v134, v34
	v_mov_b32_e32 v135, v34
	v_mov_b32_e32 v136, v34
	v_mov_b32_e32 v137, v34
	v_mov_b32_e32 v138, v34
	v_mov_b32_e32 v139, v34
	v_mov_b32_e32 v140, v34
	v_mov_b32_e32 v141, v34
	v_mov_b32_e32 v142, v34
	v_mov_b32_e32 v143, v34
	v_mov_b32_e32 v144, v34
	v_mov_b32_e32 v145, v34
	v_mov_b32_e32 v146, v34
	v_mov_b32_e32 v147, v34
	v_mov_b32_e32 v148, v34
	v_mov_b32_e32 v149, v34
	v_mov_b32_e32 v150, v34
	v_mov_b32_e32 v151, v34
	v_mov_b32_e32 v152, v34
	v_mov_b32_e32 v153, v34
	v_mov_b32_e32 v154, v34
	v_mov_b32_e32 v155, v34
	v_mov_b32_e32 v156, v34
	v_mov_b32_e32 v157, v34
	v_mov_b32_e32 v158, v34
	v_mov_b32_e32 v159, v34
	v_mov_b32_e32 v160, v34
	v_mov_b32_e32 v161, v34
	s_waitcnt lgkmcnt(0)
	s_barrier
	s_and_b32 s48, s42, 0x4000
	s_xor_b32 s44, s48, 0x4000
	s_lshl_b32 s44, s44, 1
	v_add_u32_e32 v199, s44, v185
	v_add_u32_e32 v200, s44, v186
	s_cmp_lt_u32 s43, 14
	s_cselect_b32 s45, s23, s13
	s_cselect_b32 s44, s22, s12
	s_cselect_b32 s47, s23, s21
	s_cselect_b32 s46, s22, s20
	s_lshl_b64 s[44:45], s[44:45], 1
	s_lshl_b64 s[46:47], s[46:47], 1
	s_add_u32 s50, s62, s44
	s_addc_u32 s51, s63, s45
	s_add_u32 s52, s64, s46
	s_addc_u32 s53, s65, s47
	s_lshl_b32 s44, s48, 1
	v_add_u32_e32 v228, s44, v187
	v_add_u32_e32 v229, s44, v188
	ds_read_b128 v[212:215], v229
	ds_read_b128 v[208:211], v228
	ds_read_b128 v[216:219], v229 offset:2048
	ds_read_b128 v[220:223], v229 offset:4096
	ds_read_b128 v[224:227], v229 offset:6144
	ds_read_b128 v[234:237], v228 offset:2048
	ds_read_b128 v[238:241], v228 offset:4096
	ds_read_b128 v[204:207], v228 offset:6144
	v_add_u32_e32 v229, v229, v196
; template <int MI, int NJ> ...
;     ...
;   for (int kt = 0; kt < nk; ++kt) {
;     const int buf = kt & 1;
;     {
;       G8STORE(buf ^ 1);
;       const u16* ga_ = (kt + 2 < nk) ? Ag + (kt + 2) * 64 : Ag + nAoff;
;       const u16* gb_ = (kt + 2 < nk) ? Bg + (kt + 2) * 64 : Bg + nBoff;
;       G8LOADP(ga_, gb_);
;     }
;     __builtin_amdgcn_sched_barrier(0);
;     __builtin_amdgcn_s_setprio(1);
;     const u16* a = ra_ + buf * AROWS * 64;
;     const u16* b = rb_ + buf * BROWS * 64;
; #pragma unroll
;     for (int ks = 0; ks < 2; ++ks) {
;       const u16* a_ = ks ? a + dsw : a;
;       const u16* b_ = ks ? b + dsw : b;
;       bf16x8 bfr[NJ];
; #pragma unroll
;       for (int j = 0; j < NJ; ++j) bfr[j] = *(const bf16x8*)(b_ + j * 16 * 64);
; #pragma unroll
;       for (int ih = 0; ih < MI / 4; ++ih) {
;         bf16x8 af[4];
; #pragma unroll
;         for (int i = 0; i < 4; ++i) af[i] = *(const bf16x8*)(a_ + (ih * 4 + i) * 16 * 64);
; #pragma unroll
;         for (int i = 0; i < 4; ++i)
; #pragma unroll
;           for (int j = 0; j < NJ; ++j) acc[ih * 4 + i][j] = mfma16(af[i], bfr[j], acc[ih * 4 + i][j]);
;       }
;     }
;     __builtin_amdgcn_s_setprio(0);
;     __builtin_amdgcn_sched_barrier(0);
;     __syncthreads();
;   }
.LBB0_601:
	s_setprio 1
	s_waitcnt lgkmcnt(6)
	v_mfma_f32_16x16x32_bf16 v[158:161], v[212:215], v[208:211], v[158:161]
	s_waitcnt lgkmcnt(5)
	v_mfma_f32_16x16x32_bf16 v[154:157], v[216:219], v[208:211], v[154:157]
	s_waitcnt lgkmcnt(4)
	v_mfma_f32_16x16x32_bf16 v[150:153], v[220:223], v[208:211], v[150:153]
	s_waitcnt lgkmcnt(3)
	v_mfma_f32_16x16x32_bf16 v[146:149], v[224:227], v[208:211], v[146:149]
	ds_read_b128 v[208:211], v228 offset:8192
	s_waitcnt lgkmcnt(3)
	v_mfma_f32_16x16x32_bf16 v[142:145], v[212:215], v[234:237], v[142:145]
	v_mfma_f32_16x16x32_bf16 v[138:141], v[216:219], v[234:237], v[138:141]
	v_mfma_f32_16x16x32_bf16 v[134:137], v[220:223], v[234:237], v[134:137]
	v_mfma_f32_16x16x32_bf16 v[130:133], v[224:227], v[234:237], v[130:133]
	ds_read_b128 v[234:237], v228 offset:10240
	s_waitcnt vmcnt(7)
	ds_write_b128 v199, v[2:5]
	global_load_dwordx4 v[2:5], v169, s[50:51]
	s_waitcnt lgkmcnt(4)
	v_mfma_f32_16x16x32_bf16 v[126:129], v[212:215], v[238:241], v[126:129]
	v_mfma_f32_16x16x32_bf16 v[122:125], v[216:219], v[238:241], v[122:125]
	v_mfma_f32_16x16x32_bf16 v[118:121], v[220:223], v[238:241], v[118:121]
	v_mfma_f32_16x16x32_bf16 v[114:117], v[224:227], v[238:241], v[114:117]
	ds_read_b128 v[238:241], v228 offset:12288
	s_waitcnt vmcnt(7)
	ds_write_b128 v199, v[6:9] offset:8192
	global_load_dwordx4 v[6:9], v194, s[50:51]
	ds_read_b128 v[242:245], v229
	ds_read_b128 v[246:249], v229 offset:2048
	s_waitcnt lgkmcnt(7)
	v_mfma_f32_16x16x32_bf16 v[110:113], v[212:215], v[204:207], v[110:113]
	v_mfma_f32_16x16x32_bf16 v[106:109], v[216:219], v[204:207], v[106:109]
	v_mfma_f32_16x16x32_bf16 v[102:105], v[220:223], v[204:207], v[102:105]
	v_mfma_f32_16x16x32_bf16 v[98:101], v[224:227], v[204:207], v[98:101]
	ds_read_b128 v[204:207], v228 offset:14336
	s_waitcnt vmcnt(7)
	ds_write_b128 v199, v[10:13] offset:16384
	global_load_dwordx4 v[10:13], v195, s[50:51]
	ds_read_b128 v[190:193], v229 offset:4096
	ds_read_b128 v[170:173], v229 offset:6144
	s_waitcnt lgkmcnt(10)
	v_mfma_f32_16x16x32_bf16 v[94:97], v[212:215], v[208:211], v[94:97]
	v_mfma_f32_16x16x32_bf16 v[90:93], v[216:219], v[208:211], v[90:93]
	v_mfma_f32_16x16x32_bf16 v[86:89], v[220:223], v[208:211], v[86:89]
	v_mfma_f32_16x16x32_bf16 v[82:85], v[224:227], v[208:211], v[82:85]
	v_add_u32_e32 v228, v228, v196
	ds_read_b128 v[208:211], v228
	s_waitcnt vmcnt(7)
	ds_write_b128 v199, v[18:21] offset:24576
	global_load_dwordx4 v[18:21], v198, s[50:51]
	s_waitcnt lgkmcnt(11)
	v_mfma_f32_16x16x32_bf16 v[78:81], v[212:215], v[234:237], v[78:81]
	v_mfma_f32_16x16x32_bf16 v[74:77], v[216:219], v[234:237], v[74:77]
	v_mfma_f32_16x16x32_bf16 v[70:73], v[220:223], v[234:237], v[70:73]
	v_mfma_f32_16x16x32_bf16 v[66:69], v[224:227], v[234:237], v[66:69]
	ds_read_b128 v[234:237], v228 offset:2048
	s_waitcnt vmcnt(7)
	ds_write_b128 v200, v[14:17]
	global_load_dwordx4 v[14:17], v169, s[52:53]
	s_waitcnt lgkmcnt(11)
	v_mfma_f32_16x16x32_bf16 v[62:65], v[212:215], v[238:241], v[62:65]
	v_mfma_f32_16x16x32_bf16 v[58:61], v[216:219], v[238:241], v[58:61]
	v_mfma_f32_16x16x32_bf16 v[54:57], v[220:223], v[238:241], v[54:57]
	v_mfma_f32_16x16x32_bf16 v[50:53], v[224:227], v[238:241], v[50:53]
	ds_read_b128 v[238:241], v228 offset:4096
	s_waitcnt vmcnt(7)
	ds_write_b128 v200, v[22:25] offset:8192
	global_load_dwordx4 v[22:25], v194, s[52:53]
	s_waitcnt lgkmcnt(9)
	v_mfma_f32_16x16x32_bf16 v[46:49], v[212:215], v[204:207], v[46:49]
	v_mfma_f32_16x16x32_bf16 v[42:45], v[216:219], v[204:207], v[42:45]
	v_mfma_f32_16x16x32_bf16 v[38:41], v[220:223], v[204:207], v[38:41]
	v_mfma_f32_16x16x32_bf16 v[34:37], v[224:227], v[204:207], v[34:37]
	ds_read_b128 v[204:207], v228 offset:6144
	s_waitcnt vmcnt(7)
	ds_write_b128 v200, v[26:29] offset:16384
	global_load_dwordx4 v[26:29], v195, s[52:53]
	s_waitcnt lgkmcnt(7)
	v_mfma_f32_16x16x32_bf16 v[158:161], v[242:245], v[208:211], v[158:161]
	v_mfma_f32_16x16x32_bf16 v[154:157], v[246:249], v[208:211], v[154:157]
	v_mfma_f32_16x16x32_bf16 v[150:153], v[190:193], v[208:211], v[150:153]
	v_mfma_f32_16x16x32_bf16 v[146:149], v[170:173], v[208:211], v[146:149]
	ds_read_b128 v[208:211], v228 offset:8192
	s_waitcnt vmcnt(7)
	ds_write_b128 v200, v[30:33] offset:24576
	global_load_dwordx4 v[30:33], v198, s[52:53]
	s_waitcnt lgkmcnt(7)
	v_mfma_f32_16x16x32_bf16 v[142:145], v[242:245], v[234:237], v[142:145]
	v_mfma_f32_16x16x32_bf16 v[138:141], v[246:249], v[234:237], v[138:141]
	v_mfma_f32_16x16x32_bf16 v[134:137], v[190:193], v[234:237], v[134:137]
	v_mfma_f32_16x16x32_bf16 v[130:133], v[170:173], v[234:237], v[130:133]
	ds_read_b128 v[234:237], v228 offset:10240
	s_waitcnt lgkmcnt(6)
	v_mfma_f32_16x16x32_bf16 v[126:129], v[242:245], v[238:241], v[126:129]
	v_mfma_f32_16x16x32_bf16 v[122:125], v[246:249], v[238:241], v[122:125]
	v_mfma_f32_16x16x32_bf16 v[118:121], v[190:193], v[238:241], v[118:121]
	v_mfma_f32_16x16x32_bf16 v[114:117], v[170:173], v[238:241], v[114:117]
	ds_read_b128 v[238:241], v228 offset:12288
	s_waitcnt lgkmcnt(5)
	v_mfma_f32_16x16x32_bf16 v[110:113], v[242:245], v[204:207], v[110:113]
	v_mfma_f32_16x16x32_bf16 v[106:109], v[246:249], v[204:207], v[106:109]
	v_mfma_f32_16x16x32_bf16 v[102:105], v[190:193], v[204:207], v[102:105]
	v_mfma_f32_16x16x32_bf16 v[98:101], v[170:173], v[204:207], v[98:101]
	ds_read_b128 v[204:207], v228 offset:14336
	s_waitcnt lgkmcnt(4)
	v_mfma_f32_16x16x32_bf16 v[94:97], v[242:245], v[208:211], v[94:97]
	v_mfma_f32_16x16x32_bf16 v[90:93], v[246:249], v[208:211], v[90:93]
	v_mfma_f32_16x16x32_bf16 v[86:89], v[190:193], v[208:211], v[86:89]
	v_mfma_f32_16x16x32_bf16 v[82:85], v[170:173], v[208:211], v[82:85]
	s_waitcnt lgkmcnt(0)
	s_setprio 0
	s_barrier
; __device__ __forceinline__ float siluf_(float x) { return x / (1.0f + __expf(-x)); }
; template <int MI, int NJ> ...
;     ...
;   for (int kt = 0; kt < nk; ++kt) {
;     const int buf = kt & 1;
;     {
;       G8STORE(buf ^ 1);
;       const u16* ga_ = (kt + 2 < nk) ? Ag + (kt + 2) * 64 : Ag + nAoff;
;       const u16* gb_ = (kt + 2 < nk) ? Bg + (kt + 2) * 64 : Bg + nBoff;
;       G8LOADP(ga_, gb_);
;     }
;     __builtin_amdgcn_sched_barrier(0);
;     __builtin_amdgcn_s_setprio(1);
;     const u16* a = ra_ + buf * AROWS * 64;
;     const u16* b = rb_ + buf * BROWS * 64;
; #pragma unroll
;     for (int ks = 0; ks < 2; ++ks) {
;       const u16* a_ = ks ? a + dsw : a;
;       const u16* b_ = ks ? b + dsw : b;
;       bf16x8 bfr[NJ];
; #pragma unroll
;       for (int j = 0; j < NJ; ++j) bfr[j] = *(const bf16x8*)(b_ + j * 16 * 64);
; #pragma unroll
;       for (int ih = 0; ih < MI / 4; ++ih) {
;         bf16x8 af[4];
; #pragma unroll
;         for (int i = 0; i < 4; ++i) af[i] = *(const bf16x8*)(a_ + (ih * 4 + i) * 16 * 64);
; #pragma unroll
;         for (int i = 0; i < 4; ++i)
; #pragma unroll
;           for (int j = 0; j < NJ; ++j) acc[ih * 4 + i][j] = mfma16(af[i], bfr[j], acc[ih * 4 + i][j]);
;       }
;     }
;     __builtin_amdgcn_s_setprio(0);
;     __builtin_amdgcn_sched_barrier(0);
;     __syncthreads();
;   }
; __device__ __forceinline__ void phase_ffn_up(const Params& p, const u16* Wgu, u16* smem, volatile LAS unsigned* vb_) {
;     ...
; #pragma unroll
;     for (int i = 0; i < 8; ++i)
; #pragma unroll
;       for (int jp = 0; jp < 2; ++jp) {
; #pragma unroll
;         for (int r = 0; r < 4; ++r) {
;           const float g = acc[i][2 * jp][r], u = acc[i][2 * jp + 1][r];
;           smem[(wm * 128 + i * 16 + (lane >> 4) * 4 + r) * 136 + (wn * 2 + jp) * 16 + (lane & 15)] = f2bf(siluf_(g) * u);
;         }
;         __builtin_amdgcn_sched_barrier(0);
;       }
	s_add_i32 s43, s43, 1
	s_add_u32 s22, s22, 64
	s_addc_u32 s23, s23, 0
	s_addk_i32 s42, 0x4000
	s_and_b32 s48, s42, 0x4000
	s_xor_b32 s44, s48, 0x4000
	s_lshl_b32 s44, s44, 1
	v_add_u32_e32 v199, s44, v185
	v_add_u32_e32 v200, s44, v186
	s_cmp_lt_u32 s43, 14
	s_cselect_b32 s45, s23, s13
	s_cselect_b32 s44, s22, s12
	s_cselect_b32 s47, s23, s21
	s_cselect_b32 s46, s22, s20
	s_lshl_b64 s[44:45], s[44:45], 1
	s_lshl_b64 s[46:47], s[46:47], 1
	s_add_u32 s50, s62, s44
	s_addc_u32 s51, s63, s45
	s_add_u32 s52, s64, s46
	s_addc_u32 s53, s65, s47
	s_lshl_b32 s44, s48, 1
	v_add_u32_e32 v228, s44, v187
	v_add_u32_e32 v229, s44, v188
	s_setprio 1
	ds_read_b128 v[212:215], v229
	ds_read_b128 v[208:211], v228
	ds_read_b128 v[216:219], v229 offset:2048
	ds_read_b128 v[220:223], v229 offset:4096
	ds_read_b128 v[224:227], v229 offset:6144
	v_mfma_f32_16x16x32_bf16 v[78:81], v[242:245], v[234:237], v[78:81]
	v_mfma_f32_16x16x32_bf16 v[74:77], v[246:249], v[234:237], v[74:77]
	v_mfma_f32_16x16x32_bf16 v[70:73], v[190:193], v[234:237], v[70:73]
	v_mfma_f32_16x16x32_bf16 v[66:69], v[170:173], v[234:237], v[66:69]
	ds_read_b128 v[234:237], v228 offset:2048
	v_mfma_f32_16x16x32_bf16 v[62:65], v[242:245], v[238:241], v[62:65]
	v_mfma_f32_16x16x32_bf16 v[58:61], v[246:249], v[238:241], v[58:61]
	v_mfma_f32_16x16x32_bf16 v[54:57], v[190:193], v[238:241], v[54:57]
	v_mfma_f32_16x16x32_bf16 v[50:53], v[170:173], v[238:241], v[50:53]
	ds_read_b128 v[238:241], v228 offset:4096
	v_mfma_f32_16x16x32_bf16 v[46:49], v[242:245], v[204:207], v[46:49]
	v_mfma_f32_16x16x32_bf16 v[42:45], v[246:249], v[204:207], v[42:45]
	v_mfma_f32_16x16x32_bf16 v[38:41], v[190:193], v[204:207], v[38:41]
	v_mfma_f32_16x16x32_bf16 v[34:37], v[170:173], v[204:207], v[34:37]
	ds_read_b128 v[204:207], v228 offset:6144
	v_add_u32_e32 v229, v229, v196
	s_setprio 0
	s_cmpk_lg_i32 s22, 0x480
	s_cbranch_scc1 .LBB0_601
	v_and_b32_e32 v228, 15, v175
	v_bfe_u32 v229, v175, 8, 1
	v_lshl_or_b32 v228, v229, 7, v228
	v_mul_u32_u24_e32 v228, 0x110, v228
	v_bfe_u32 v229, v175, 6, 2
	v_lshl_add_u32 v228, v229, 6, v228
	v_bfe_u32 v229, v175, 4, 2
	v_lshl_add_u32 v228, v229, 3, v228
	v_mul_f32_e32 v208, 0xbfb8aa3b, v158
	v_mul_f32_e32 v209, 0xbfb8aa3b, v159
	v_mul_f32_e32 v210, 0xbfb8aa3b, v160
	v_mul_f32_e32 v211, 0xbfb8aa3b, v161
	v_mul_f32_e32 v212, 0xbfb8aa3b, v150
	v_mul_f32_e32 v213, 0xbfb8aa3b, v151
	v_mul_f32_e32 v214, 0xbfb8aa3b, v152
	v_mul_f32_e32 v215, 0xbfb8aa3b, v153
	v_min_f32_e32 v208, 0x42fc0000, v208
	v_min_f32_e32 v209, 0x42fc0000, v209
	v_min_f32_e32 v210, 0x42fc0000, v210
	v_min_f32_e32 v211, 0x42fc0000, v211
	v_min_f32_e32 v212, 0x42fc0000, v212
	v_min_f32_e32 v213, 0x42fc0000, v213
	v_min_f32_e32 v214, 0x42fc0000, v214
	v_min_f32_e32 v215, 0x42fc0000, v215
	v_exp_f32_e32 v208, v208
	v_exp_f32_e32 v209, v209
	v_exp_f32_e32 v210, v210
	v_exp_f32_e32 v211, v211
	v_exp_f32_e32 v212, v212
	v_exp_f32_e32 v213, v213
	v_exp_f32_e32 v214, v214
	v_exp_f32_e32 v215, v215
	v_add_f32_e32 v208, 1.0, v208
	v_add_f32_e32 v209, 1.0, v209
	v_add_f32_e32 v210, 1.0, v210
	v_add_f32_e32 v211, 1.0, v211
	v_add_f32_e32 v212, 1.0, v212
	v_add_f32_e32 v213, 1.0, v213
	v_add_f32_e32 v214, 1.0, v214
	v_add_f32_e32 v215, 1.0, v215
	v_rcp_f32_e32 v216, v208
	v_rcp_f32_e32 v217, v209
	v_rcp_f32_e32 v218, v210
	v_rcp_f32_e32 v219, v211
	v_rcp_f32_e32 v220, v212
	v_rcp_f32_e32 v221, v213
	v_rcp_f32_e32 v222, v214
	v_rcp_f32_e32 v223, v215
	v_fma_f32 v208, -v208, v216, 1.0
	v_fma_f32 v209, -v209, v217, 1.0
	v_fma_f32 v210, -v210, v218, 1.0
	v_fma_f32 v211, -v211, v219, 1.0
	v_fma_f32 v212, -v212, v220, 1.0
	v_fma_f32 v213, -v213, v221, 1.0
	v_fma_f32 v214, -v214, v222, 1.0
	v_fma_f32 v215, -v215, v223, 1.0
	v_fmac_f32_e32 v216, v208, v216
	v_fmac_f32_e32 v217, v209, v217
	v_fmac_f32_e32 v218, v210, v218
	v_fmac_f32_e32 v219, v211, v219
	v_fmac_f32_e32 v220, v212, v220
	v_fmac_f32_e32 v221, v213, v221
	v_fmac_f32_e32 v222, v214, v222
	v_fmac_f32_e32 v223, v215, v223
	v_mul_f32_e32 v158, v158, v216
	v_mul_f32_e32 v159, v159, v217
	v_mul_f32_e32 v160, v160, v218
	v_mul_f32_e32 v161, v161, v219
	v_mul_f32_e32 v150, v150, v220
	v_mul_f32_e32 v151, v151, v221
	v_mul_f32_e32 v152, v152, v222
	v_mul_f32_e32 v153, v153, v223
	v_mul_f32_e32 v158, v158, v154
	v_mul_f32_e32 v159, v159, v155
	v_mul_f32_e32 v160, v160, v156
	v_mul_f32_e32 v161, v161, v157
	v_mul_f32_e32 v150, v150, v146
	v_mul_f32_e32 v151, v151, v147
	v_mul_f32_e32 v152, v152, v148
	v_mul_f32_e32 v153, v153, v149
	v_cvt_pk_bf16_f32 v158, v158, v159
	v_cvt_pk_bf16_f32 v159, v160, v161
	v_cvt_pk_bf16_f32 v150, v150, v151
	v_cvt_pk_bf16_f32 v151, v152, v153
	ds_write_b64 v228, v[158:159]
	ds_write_b64 v228, v[150:151] offset:32
	v_mul_f32_e32 v208, 0xbfb8aa3b, v142
	v_mul_f32_e32 v209, 0xbfb8aa3b, v143
	v_mul_f32_e32 v210, 0xbfb8aa3b, v144
	v_mul_f32_e32 v211, 0xbfb8aa3b, v145
	v_mul_f32_e32 v212, 0xbfb8aa3b, v134
	v_mul_f32_e32 v213, 0xbfb8aa3b, v135
	v_mul_f32_e32 v214, 0xbfb8aa3b, v136
	v_mul_f32_e32 v215, 0xbfb8aa3b, v137
	v_min_f32_e32 v208, 0x42fc0000, v208
	v_min_f32_e32 v209, 0x42fc0000, v209
	v_min_f32_e32 v210, 0x42fc0000, v210
	v_min_f32_e32 v211, 0x42fc0000, v211
	v_min_f32_e32 v212, 0x42fc0000, v212
	v_min_f32_e32 v213, 0x42fc0000, v213
	v_min_f32_e32 v214, 0x42fc0000, v214
	v_min_f32_e32 v215, 0x42fc0000, v215
	v_exp_f32_e32 v208, v208
	v_exp_f32_e32 v209, v209
	v_exp_f32_e32 v210, v210
	v_exp_f32_e32 v211, v211
	v_exp_f32_e32 v212, v212
	v_exp_f32_e32 v213, v213
	v_exp_f32_e32 v214, v214
	v_exp_f32_e32 v215, v215
	v_add_f32_e32 v208, 1.0, v208
	v_add_f32_e32 v209, 1.0, v209
	v_add_f32_e32 v210, 1.0, v210
	v_add_f32_e32 v211, 1.0, v211
	v_add_f32_e32 v212, 1.0, v212
; __device__ __forceinline__ float siluf_(float x) { return x / (1.0f + __expf(-x)); }
; __device__ __forceinline__ void phase_ffn_up(const Params& p, const u16* Wgu, u16* smem, volatile LAS unsigned* vb_) {
;     ...
; #pragma unroll
;     for (int i = 0; i < 8; ++i)
; #pragma unroll
;       for (int jp = 0; jp < 2; ++jp) {
; #pragma unroll
;         for (int r = 0; r < 4; ++r) {
;           const float g = acc[i][2 * jp][r], u = acc[i][2 * jp + 1][r];
;           smem[(wm * 128 + i * 16 + (lane >> 4) * 4 + r) * 136 + (wn * 2 + jp) * 16 + (lane & 15)] = f2bf(siluf_(g) * u);
;         }
;         __builtin_amdgcn_sched_barrier(0);
;       }
	v_add_f32_e32 v213, 1.0, v213
	v_add_f32_e32 v214, 1.0, v214
	v_add_f32_e32 v215, 1.0, v215
	v_rcp_f32_e32 v216, v208
	v_rcp_f32_e32 v217, v209
	v_rcp_f32_e32 v218, v210
	v_rcp_f32_e32 v219, v211
	v_rcp_f32_e32 v220, v212
	v_rcp_f32_e32 v221, v213
	v_rcp_f32_e32 v222, v214
	v_rcp_f32_e32 v223, v215
	v_fma_f32 v208, -v208, v216, 1.0
	v_fma_f32 v209, -v209, v217, 1.0
	v_fma_f32 v210, -v210, v218, 1.0
	v_fma_f32 v211, -v211, v219, 1.0
	v_fma_f32 v212, -v212, v220, 1.0
	v_fma_f32 v213, -v213, v221, 1.0
	v_fma_f32 v214, -v214, v222, 1.0
	v_fma_f32 v215, -v215, v223, 1.0
	v_fmac_f32_e32 v216, v208, v216
	v_fmac_f32_e32 v217, v209, v217
	v_fmac_f32_e32 v218, v210, v218
	v_fmac_f32_e32 v219, v211, v219
	v_fmac_f32_e32 v220, v212, v220
	v_fmac_f32_e32 v221, v213, v221
	v_fmac_f32_e32 v222, v214, v222
	v_fmac_f32_e32 v223, v215, v223
	v_mul_f32_e32 v142, v142, v216
	v_mul_f32_e32 v143, v143, v217
	v_mul_f32_e32 v144, v144, v218
	v_mul_f32_e32 v145, v145, v219
	v_mul_f32_e32 v134, v134, v220
	v_mul_f32_e32 v135, v135, v221
	v_mul_f32_e32 v136, v136, v222
	v_mul_f32_e32 v137, v137, v223
	v_mul_f32_e32 v142, v142, v138
	v_mul_f32_e32 v143, v143, v139
	v_mul_f32_e32 v144, v144, v140
	v_mul_f32_e32 v145, v145, v141
	v_mul_f32_e32 v134, v134, v130
	v_mul_f32_e32 v135, v135, v131
	v_mul_f32_e32 v136, v136, v132
	v_mul_f32_e32 v137, v137, v133
	v_cvt_pk_bf16_f32 v142, v142, v143
	v_cvt_pk_bf16_f32 v143, v144, v145
	v_cvt_pk_bf16_f32 v134, v134, v135
	v_cvt_pk_bf16_f32 v135, v136, v137
	ds_write_b64 v228, v[142:143] offset:4352
	ds_write_b64 v228, v[134:135] offset:4384
	v_mul_f32_e32 v208, 0xbfb8aa3b, v126
	v_mul_f32_e32 v209, 0xbfb8aa3b, v127
	v_mul_f32_e32 v210, 0xbfb8aa3b, v128
	v_mul_f32_e32 v211, 0xbfb8aa3b, v129
	v_mul_f32_e32 v212, 0xbfb8aa3b, v118
	v_mul_f32_e32 v213, 0xbfb8aa3b, v119
	v_mul_f32_e32 v214, 0xbfb8aa3b, v120
	v_mul_f32_e32 v215, 0xbfb8aa3b, v121
	v_min_f32_e32 v208, 0x42fc0000, v208
	v_min_f32_e32 v209, 0x42fc0000, v209
	v_min_f32_e32 v210, 0x42fc0000, v210
	v_min_f32_e32 v211, 0x42fc0000, v211
	v_min_f32_e32 v212, 0x42fc0000, v212
	v_min_f32_e32 v213, 0x42fc0000, v213
	v_min_f32_e32 v214, 0x42fc0000, v214
	v_min_f32_e32 v215, 0x42fc0000, v215
	v_exp_f32_e32 v208, v208
	v_exp_f32_e32 v209, v209
	v_exp_f32_e32 v210, v210
	v_exp_f32_e32 v211, v211
	v_exp_f32_e32 v212, v212
	v_exp_f32_e32 v213, v213
	v_exp_f32_e32 v214, v214
	v_exp_f32_e32 v215, v215
	v_add_f32_e32 v208, 1.0, v208
	v_add_f32_e32 v209, 1.0, v209
	v_add_f32_e32 v210, 1.0, v210
	v_add_f32_e32 v211, 1.0, v211
	v_add_f32_e32 v212, 1.0, v212
	v_add_f32_e32 v213, 1.0, v213
	v_add_f32_e32 v214, 1.0, v214
	v_add_f32_e32 v215, 1.0, v215
	v_rcp_f32_e32 v216, v208
	v_rcp_f32_e32 v217, v209
	v_rcp_f32_e32 v218, v210
	v_rcp_f32_e32 v219, v211
	v_rcp_f32_e32 v220, v212
	v_rcp_f32_e32 v221, v213
	v_rcp_f32_e32 v222, v214
	v_rcp_f32_e32 v223, v215
	v_fma_f32 v208, -v208, v216, 1.0
	v_fma_f32 v209, -v209, v217, 1.0
	v_fma_f32 v210, -v210, v218, 1.0
	v_fma_f32 v211, -v211, v219, 1.0
	v_fma_f32 v212, -v212, v220, 1.0
	v_fma_f32 v213, -v213, v221, 1.0
	v_fma_f32 v214, -v214, v222, 1.0
	v_fma_f32 v215, -v215, v223, 1.0
	v_fmac_f32_e32 v216, v208, v216
	v_fmac_f32_e32 v217, v209, v217
	v_fmac_f32_e32 v218, v210, v218
	v_fmac_f32_e32 v219, v211, v219
	v_fmac_f32_e32 v220, v212, v220
	v_fmac_f32_e32 v221, v213, v221
	v_fmac_f32_e32 v222, v214, v222
	v_fmac_f32_e32 v223, v215, v223
	v_mul_f32_e32 v126, v126, v216
	v_mul_f32_e32 v127, v127, v217
	v_mul_f32_e32 v128, v128, v218
	v_mul_f32_e32 v129, v129, v219
	v_mul_f32_e32 v118, v118, v220
	v_mul_f32_e32 v119, v119, v221
	v_mul_f32_e32 v120, v120, v222
	v_mul_f32_e32 v121, v121, v223
	v_mul_f32_e32 v126, v126, v122
	v_mul_f32_e32 v127, v127, v123
	v_mul_f32_e32 v128, v128, v124
	v_mul_f32_e32 v129, v129, v125
	v_mul_f32_e32 v118, v118, v114
	v_mul_f32_e32 v119, v119, v115
	v_mul_f32_e32 v120, v120, v116
	v_mul_f32_e32 v121, v121, v117
	v_cvt_pk_bf16_f32 v126, v126, v127
	v_cvt_pk_bf16_f32 v127, v128, v129
	v_cvt_pk_bf16_f32 v118, v118, v119
	v_cvt_pk_bf16_f32 v119, v120, v121
	ds_write_b64 v228, v[126:127] offset:8704
	ds_write_b64 v228, v[118:119] offset:8736
	v_mul_f32_e32 v208, 0xbfb8aa3b, v110
	v_mul_f32_e32 v209, 0xbfb8aa3b, v111
	v_mul_f32_e32 v210, 0xbfb8aa3b, v112
	v_mul_f32_e32 v211, 0xbfb8aa3b, v113
	v_mul_f32_e32 v212, 0xbfb8aa3b, v102
	v_mul_f32_e32 v213, 0xbfb8aa3b, v103
	v_mul_f32_e32 v214, 0xbfb8aa3b, v104
	v_mul_f32_e32 v215, 0xbfb8aa3b, v105
	v_min_f32_e32 v208, 0x42fc0000, v208
	v_min_f32_e32 v209, 0x42fc0000, v209
	v_min_f32_e32 v210, 0x42fc0000, v210
	v_min_f32_e32 v211, 0x42fc0000, v211
	v_min_f32_e32 v212, 0x42fc0000, v212
	v_min_f32_e32 v213, 0x42fc0000, v213
	v_min_f32_e32 v214, 0x42fc0000, v214
	v_min_f32_e32 v215, 0x42fc0000, v215
	v_exp_f32_e32 v208, v208
	v_exp_f32_e32 v209, v209
	v_exp_f32_e32 v210, v210
	v_exp_f32_e32 v211, v211
	v_exp_f32_e32 v212, v212
	v_exp_f32_e32 v213, v213
	v_exp_f32_e32 v214, v214
	v_exp_f32_e32 v215, v215
	v_add_f32_e32 v208, 1.0, v208
	v_add_f32_e32 v209, 1.0, v209
	v_add_f32_e32 v210, 1.0, v210
	v_add_f32_e32 v211, 1.0, v211
	v_add_f32_e32 v212, 1.0, v212
	v_add_f32_e32 v213, 1.0, v213
	v_add_f32_e32 v214, 1.0, v214
	v_add_f32_e32 v215, 1.0, v215
	v_rcp_f32_e32 v216, v208
	v_rcp_f32_e32 v217, v209
	v_rcp_f32_e32 v218, v210
	v_rcp_f32_e32 v219, v211
	v_rcp_f32_e32 v220, v212
	v_rcp_f32_e32 v221, v213
	v_rcp_f32_e32 v222, v214
	v_rcp_f32_e32 v223, v215
	v_fma_f32 v208, -v208, v216, 1.0
	v_fma_f32 v209, -v209, v217, 1.0
	v_fma_f32 v210, -v210, v218, 1.0
	v_fma_f32 v211, -v211, v219, 1.0
	v_fma_f32 v212, -v212, v220, 1.0
	v_fma_f32 v213, -v213, v221, 1.0
	v_fma_f32 v214, -v214, v222, 1.0
; __device__ __forceinline__ float siluf_(float x) { return x / (1.0f + __expf(-x)); }
; __device__ __forceinline__ void phase_ffn_up(const Params& p, const u16* Wgu, u16* smem, volatile LAS unsigned* vb_) {
;     ...
; #pragma unroll
;     for (int i = 0; i < 8; ++i)
; #pragma unroll
;       for (int jp = 0; jp < 2; ++jp) {
; #pragma unroll
;         for (int r = 0; r < 4; ++r) {
;           const float g = acc[i][2 * jp][r], u = acc[i][2 * jp + 1][r];
;           smem[(wm * 128 + i * 16 + (lane >> 4) * 4 + r) * 136 + (wn * 2 + jp) * 16 + (lane & 15)] = f2bf(siluf_(g) * u);
;         }
;         __builtin_amdgcn_sched_barrier(0);
;       }
	v_fma_f32 v215, -v215, v223, 1.0
	v_fmac_f32_e32 v216, v208, v216
	v_fmac_f32_e32 v217, v209, v217
	v_fmac_f32_e32 v218, v210, v218
	v_fmac_f32_e32 v219, v211, v219
	v_fmac_f32_e32 v220, v212, v220
	v_fmac_f32_e32 v221, v213, v221
	v_fmac_f32_e32 v222, v214, v222
	v_fmac_f32_e32 v223, v215, v223
	v_mul_f32_e32 v110, v110, v216
	v_mul_f32_e32 v111, v111, v217
	v_mul_f32_e32 v112, v112, v218
	v_mul_f32_e32 v113, v113, v219
	v_mul_f32_e32 v102, v102, v220
	v_mul_f32_e32 v103, v103, v221
	v_mul_f32_e32 v104, v104, v222
	v_mul_f32_e32 v105, v105, v223
	v_mul_f32_e32 v110, v110, v106
	v_mul_f32_e32 v111, v111, v107
	v_mul_f32_e32 v112, v112, v108
	v_mul_f32_e32 v113, v113, v109
	v_mul_f32_e32 v102, v102, v98
	v_mul_f32_e32 v103, v103, v99
	v_mul_f32_e32 v104, v104, v100
	v_mul_f32_e32 v105, v105, v101
	v_cvt_pk_bf16_f32 v110, v110, v111
	v_cvt_pk_bf16_f32 v111, v112, v113
	v_cvt_pk_bf16_f32 v102, v102, v103
	v_cvt_pk_bf16_f32 v103, v104, v105
	ds_write_b64 v228, v[110:111] offset:13056
	ds_write_b64 v228, v[102:103] offset:13088
	v_mul_f32_e32 v208, 0xbfb8aa3b, v94
	v_mul_f32_e32 v209, 0xbfb8aa3b, v95
	v_mul_f32_e32 v210, 0xbfb8aa3b, v96
	v_mul_f32_e32 v211, 0xbfb8aa3b, v97
	v_mul_f32_e32 v212, 0xbfb8aa3b, v86
	v_mul_f32_e32 v213, 0xbfb8aa3b, v87
	v_mul_f32_e32 v214, 0xbfb8aa3b, v88
	v_mul_f32_e32 v215, 0xbfb8aa3b, v89
	v_min_f32_e32 v208, 0x42fc0000, v208
	v_min_f32_e32 v209, 0x42fc0000, v209
	v_min_f32_e32 v210, 0x42fc0000, v210
	v_min_f32_e32 v211, 0x42fc0000, v211
	v_min_f32_e32 v212, 0x42fc0000, v212
	v_min_f32_e32 v213, 0x42fc0000, v213
	v_min_f32_e32 v214, 0x42fc0000, v214
	v_min_f32_e32 v215, 0x42fc0000, v215
	v_exp_f32_e32 v208, v208
	v_exp_f32_e32 v209, v209
	v_exp_f32_e32 v210, v210
	v_exp_f32_e32 v211, v211
	v_exp_f32_e32 v212, v212
	v_exp_f32_e32 v213, v213
	v_exp_f32_e32 v214, v214
	v_exp_f32_e32 v215, v215
	v_add_f32_e32 v208, 1.0, v208
	v_add_f32_e32 v209, 1.0, v209
	v_add_f32_e32 v210, 1.0, v210
	v_add_f32_e32 v211, 1.0, v211
	v_add_f32_e32 v212, 1.0, v212
	v_add_f32_e32 v213, 1.0, v213
	v_add_f32_e32 v214, 1.0, v214
	v_add_f32_e32 v215, 1.0, v215
	v_rcp_f32_e32 v216, v208
	v_rcp_f32_e32 v217, v209
	v_rcp_f32_e32 v218, v210
	v_rcp_f32_e32 v219, v211
	v_rcp_f32_e32 v220, v212
	v_rcp_f32_e32 v221, v213
	v_rcp_f32_e32 v222, v214
	v_rcp_f32_e32 v223, v215
	v_fma_f32 v208, -v208, v216, 1.0
	v_fma_f32 v209, -v209, v217, 1.0
	v_fma_f32 v210, -v210, v218, 1.0
	v_fma_f32 v211, -v211, v219, 1.0
	v_fma_f32 v212, -v212, v220, 1.0
	v_fma_f32 v213, -v213, v221, 1.0
	v_fma_f32 v214, -v214, v222, 1.0
	v_fma_f32 v215, -v215, v223, 1.0
	v_fmac_f32_e32 v216, v208, v216
	v_fmac_f32_e32 v217, v209, v217
	v_fmac_f32_e32 v218, v210, v218
	v_fmac_f32_e32 v219, v211, v219
	v_fmac_f32_e32 v220, v212, v220
	v_fmac_f32_e32 v221, v213, v221
	v_fmac_f32_e32 v222, v214, v222
	v_fmac_f32_e32 v223, v215, v223
	v_mul_f32_e32 v94, v94, v216
	v_mul_f32_e32 v95, v95, v217
	v_mul_f32_e32 v96, v96, v218
	v_mul_f32_e32 v97, v97, v219
	v_mul_f32_e32 v86, v86, v220
	v_mul_f32_e32 v87, v87, v221
	v_mul_f32_e32 v88, v88, v222
	v_mul_f32_e32 v89, v89, v223
	v_mul_f32_e32 v94, v94, v90
	v_mul_f32_e32 v95, v95, v91
	v_mul_f32_e32 v96, v96, v92
	v_mul_f32_e32 v97, v97, v93
	v_mul_f32_e32 v86, v86, v82
	v_mul_f32_e32 v87, v87, v83
	v_mul_f32_e32 v88, v88, v84
	v_mul_f32_e32 v89, v89, v85
	v_cvt_pk_bf16_f32 v94, v94, v95
	v_cvt_pk_bf16_f32 v95, v96, v97
	v_cvt_pk_bf16_f32 v86, v86, v87
	v_cvt_pk_bf16_f32 v87, v88, v89
	ds_write_b64 v228, v[94:95] offset:17408
	ds_write_b64 v228, v[86:87] offset:17440
	v_mul_f32_e32 v208, 0xbfb8aa3b, v78
	v_mul_f32_e32 v209, 0xbfb8aa3b, v79
	v_mul_f32_e32 v210, 0xbfb8aa3b, v80
	v_mul_f32_e32 v211, 0xbfb8aa3b, v81
	v_mul_f32_e32 v212, 0xbfb8aa3b, v70
	v_mul_f32_e32 v213, 0xbfb8aa3b, v71
	v_mul_f32_e32 v214, 0xbfb8aa3b, v72
	v_mul_f32_e32 v215, 0xbfb8aa3b, v73
	v_min_f32_e32 v208, 0x42fc0000, v208
	v_min_f32_e32 v209, 0x42fc0000, v209
	v_min_f32_e32 v210, 0x42fc0000, v210
	v_min_f32_e32 v211, 0x42fc0000, v211
	v_min_f32_e32 v212, 0x42fc0000, v212
	v_min_f32_e32 v213, 0x42fc0000, v213
	v_min_f32_e32 v214, 0x42fc0000, v214
	v_min_f32_e32 v215, 0x42fc0000, v215
	v_exp_f32_e32 v208, v208
	v_exp_f32_e32 v209, v209
	v_exp_f32_e32 v210, v210
	v_exp_f32_e32 v211, v211
	v_exp_f32_e32 v212, v212
	v_exp_f32_e32 v213, v213
	v_exp_f32_e32 v214, v214
	v_exp_f32_e32 v215, v215
	v_add_f32_e32 v208, 1.0, v208
	v_add_f32_e32 v209, 1.0, v209
	v_add_f32_e32 v210, 1.0, v210
	v_add_f32_e32 v211, 1.0, v211
	v_add_f32_e32 v212, 1.0, v212
	v_add_f32_e32 v213, 1.0, v213
	v_add_f32_e32 v214, 1.0, v214
	v_add_f32_e32 v215, 1.0, v215
	v_rcp_f32_e32 v216, v208
	v_rcp_f32_e32 v217, v209
	v_rcp_f32_e32 v218, v210
	v_rcp_f32_e32 v219, v211
	v_rcp_f32_e32 v220, v212
	v_rcp_f32_e32 v221, v213
	v_rcp_f32_e32 v222, v214
	v_rcp_f32_e32 v223, v215
	v_fma_f32 v208, -v208, v216, 1.0
	v_fma_f32 v209, -v209, v217, 1.0
	v_fma_f32 v210, -v210, v218, 1.0
	v_fma_f32 v211, -v211, v219, 1.0
	v_fma_f32 v212, -v212, v220, 1.0
	v_fma_f32 v213, -v213, v221, 1.0
	v_fma_f32 v214, -v214, v222, 1.0
	v_fma_f32 v215, -v215, v223, 1.0
	v_fmac_f32_e32 v216, v208, v216
	v_fmac_f32_e32 v217, v209, v217
	v_fmac_f32_e32 v218, v210, v218
	v_fmac_f32_e32 v219, v211, v219
	v_fmac_f32_e32 v220, v212, v220
	v_fmac_f32_e32 v221, v213, v221
	v_fmac_f32_e32 v222, v214, v222
	v_fmac_f32_e32 v223, v215, v223
	v_mul_f32_e32 v78, v78, v216
	v_mul_f32_e32 v79, v79, v217
	v_mul_f32_e32 v80, v80, v218
	v_mul_f32_e32 v81, v81, v219
	v_mul_f32_e32 v70, v70, v220
	v_mul_f32_e32 v71, v71, v221
	v_mul_f32_e32 v72, v72, v222
	v_mul_f32_e32 v73, v73, v223
	v_mul_f32_e32 v78, v78, v74
	v_mul_f32_e32 v79, v79, v75
; __device__ __forceinline__ float siluf_(float x) { return x / (1.0f + __expf(-x)); }
; __device__ __forceinline__ void phase_ffn_up(const Params& p, const u16* Wgu, u16* smem, volatile LAS unsigned* vb_) {
;     ...
; #pragma unroll
;     for (int i = 0; i < 8; ++i)
; #pragma unroll
;       for (int jp = 0; jp < 2; ++jp) {
; #pragma unroll
;         for (int r = 0; r < 4; ++r) {
;           const float g = acc[i][2 * jp][r], u = acc[i][2 * jp + 1][r];
;           smem[(wm * 128 + i * 16 + (lane >> 4) * 4 + r) * 136 + (wn * 2 + jp) * 16 + (lane & 15)] = f2bf(siluf_(g) * u);
;         }
;         __builtin_amdgcn_sched_barrier(0);
;       }
;     __syncthreads();
	v_mul_f32_e32 v80, v80, v76
	v_mul_f32_e32 v81, v81, v77
	v_mul_f32_e32 v70, v70, v66
	v_mul_f32_e32 v71, v71, v67
	v_mul_f32_e32 v72, v72, v68
	v_mul_f32_e32 v73, v73, v69
	v_cvt_pk_bf16_f32 v78, v78, v79
	v_cvt_pk_bf16_f32 v79, v80, v81
	v_cvt_pk_bf16_f32 v70, v70, v71
	v_cvt_pk_bf16_f32 v71, v72, v73
	ds_write_b64 v228, v[78:79] offset:21760
	ds_write_b64 v228, v[70:71] offset:21792
	v_mul_f32_e32 v208, 0xbfb8aa3b, v62
	v_mul_f32_e32 v209, 0xbfb8aa3b, v63
	v_mul_f32_e32 v210, 0xbfb8aa3b, v64
	v_mul_f32_e32 v211, 0xbfb8aa3b, v65
	v_mul_f32_e32 v212, 0xbfb8aa3b, v54
	v_mul_f32_e32 v213, 0xbfb8aa3b, v55
	v_mul_f32_e32 v214, 0xbfb8aa3b, v56
	v_mul_f32_e32 v215, 0xbfb8aa3b, v57
	v_min_f32_e32 v208, 0x42fc0000, v208
	v_min_f32_e32 v209, 0x42fc0000, v209
	v_min_f32_e32 v210, 0x42fc0000, v210
	v_min_f32_e32 v211, 0x42fc0000, v211
	v_min_f32_e32 v212, 0x42fc0000, v212
	v_min_f32_e32 v213, 0x42fc0000, v213
	v_min_f32_e32 v214, 0x42fc0000, v214
	v_min_f32_e32 v215, 0x42fc0000, v215
	v_exp_f32_e32 v208, v208
	v_exp_f32_e32 v209, v209
	v_exp_f32_e32 v210, v210
	v_exp_f32_e32 v211, v211
	v_exp_f32_e32 v212, v212
	v_exp_f32_e32 v213, v213
	v_exp_f32_e32 v214, v214
	v_exp_f32_e32 v215, v215
	v_add_f32_e32 v208, 1.0, v208
	v_add_f32_e32 v209, 1.0, v209
	v_add_f32_e32 v210, 1.0, v210
	v_add_f32_e32 v211, 1.0, v211
	v_add_f32_e32 v212, 1.0, v212
	v_add_f32_e32 v213, 1.0, v213
	v_add_f32_e32 v214, 1.0, v214
	v_add_f32_e32 v215, 1.0, v215
	v_rcp_f32_e32 v216, v208
	v_rcp_f32_e32 v217, v209
	v_rcp_f32_e32 v218, v210
	v_rcp_f32_e32 v219, v211
	v_rcp_f32_e32 v220, v212
	v_rcp_f32_e32 v221, v213
	v_rcp_f32_e32 v222, v214
	v_rcp_f32_e32 v223, v215
	v_fma_f32 v208, -v208, v216, 1.0
	v_fma_f32 v209, -v209, v217, 1.0
	v_fma_f32 v210, -v210, v218, 1.0
	v_fma_f32 v211, -v211, v219, 1.0
	v_fma_f32 v212, -v212, v220, 1.0
	v_fma_f32 v213, -v213, v221, 1.0
	v_fma_f32 v214, -v214, v222, 1.0
	v_fma_f32 v215, -v215, v223, 1.0
	v_fmac_f32_e32 v216, v208, v216
	v_fmac_f32_e32 v217, v209, v217
	v_fmac_f32_e32 v218, v210, v218
	v_fmac_f32_e32 v219, v211, v219
	v_fmac_f32_e32 v220, v212, v220
	v_fmac_f32_e32 v221, v213, v221
	v_fmac_f32_e32 v222, v214, v222
	v_fmac_f32_e32 v223, v215, v223
	v_mul_f32_e32 v62, v62, v216
	v_mul_f32_e32 v63, v63, v217
	v_mul_f32_e32 v64, v64, v218
	v_mul_f32_e32 v65, v65, v219
	v_mul_f32_e32 v54, v54, v220
	v_mul_f32_e32 v55, v55, v221
	v_mul_f32_e32 v56, v56, v222
	v_mul_f32_e32 v57, v57, v223
	v_mul_f32_e32 v62, v62, v58
	v_mul_f32_e32 v63, v63, v59
	v_mul_f32_e32 v64, v64, v60
	v_mul_f32_e32 v65, v65, v61
	v_mul_f32_e32 v54, v54, v50
	v_mul_f32_e32 v55, v55, v51
	v_mul_f32_e32 v56, v56, v52
	v_mul_f32_e32 v57, v57, v53
	v_cvt_pk_bf16_f32 v62, v62, v63
	v_cvt_pk_bf16_f32 v63, v64, v65
	v_cvt_pk_bf16_f32 v54, v54, v55
	v_cvt_pk_bf16_f32 v55, v56, v57
	ds_write_b64 v228, v[62:63] offset:26112
	ds_write_b64 v228, v[54:55] offset:26144
	v_mul_f32_e32 v208, 0xbfb8aa3b, v46
	v_mul_f32_e32 v209, 0xbfb8aa3b, v47
	v_mul_f32_e32 v210, 0xbfb8aa3b, v48
	v_mul_f32_e32 v211, 0xbfb8aa3b, v49
	v_mul_f32_e32 v212, 0xbfb8aa3b, v38
	v_mul_f32_e32 v213, 0xbfb8aa3b, v39
	v_mul_f32_e32 v214, 0xbfb8aa3b, v40
	v_mul_f32_e32 v215, 0xbfb8aa3b, v41
	v_min_f32_e32 v208, 0x42fc0000, v208
	v_min_f32_e32 v209, 0x42fc0000, v209
	v_min_f32_e32 v210, 0x42fc0000, v210
	v_min_f32_e32 v211, 0x42fc0000, v211
	v_min_f32_e32 v212, 0x42fc0000, v212
	v_min_f32_e32 v213, 0x42fc0000, v213
	v_min_f32_e32 v214, 0x42fc0000, v214
	v_min_f32_e32 v215, 0x42fc0000, v215
	v_exp_f32_e32 v208, v208
	v_exp_f32_e32 v209, v209
	v_exp_f32_e32 v210, v210
	v_exp_f32_e32 v211, v211
	v_exp_f32_e32 v212, v212
	v_exp_f32_e32 v213, v213
	v_exp_f32_e32 v214, v214
	v_exp_f32_e32 v215, v215
	v_add_f32_e32 v208, 1.0, v208
	v_add_f32_e32 v209, 1.0, v209
	v_add_f32_e32 v210, 1.0, v210
	v_add_f32_e32 v211, 1.0, v211
	v_add_f32_e32 v212, 1.0, v212
	v_add_f32_e32 v213, 1.0, v213
	v_add_f32_e32 v214, 1.0, v214
	v_add_f32_e32 v215, 1.0, v215
	v_rcp_f32_e32 v216, v208
	v_rcp_f32_e32 v217, v209
	v_rcp_f32_e32 v218, v210
	v_rcp_f32_e32 v219, v211
	v_rcp_f32_e32 v220, v212
	v_rcp_f32_e32 v221, v213
	v_rcp_f32_e32 v222, v214
	v_rcp_f32_e32 v223, v215
	v_fma_f32 v208, -v208, v216, 1.0
	v_fma_f32 v209, -v209, v217, 1.0
	v_fma_f32 v210, -v210, v218, 1.0
	v_fma_f32 v211, -v211, v219, 1.0
	v_fma_f32 v212, -v212, v220, 1.0
	v_fma_f32 v213, -v213, v221, 1.0
	v_fma_f32 v214, -v214, v222, 1.0
	v_fma_f32 v215, -v215, v223, 1.0
	v_fmac_f32_e32 v216, v208, v216
	v_fmac_f32_e32 v217, v209, v217
	v_fmac_f32_e32 v218, v210, v218
	v_fmac_f32_e32 v219, v211, v219
	v_fmac_f32_e32 v220, v212, v220
	v_fmac_f32_e32 v221, v213, v221
	v_fmac_f32_e32 v222, v214, v222
	v_fmac_f32_e32 v223, v215, v223
	v_mul_f32_e32 v46, v46, v216
	v_mul_f32_e32 v47, v47, v217
	v_mul_f32_e32 v48, v48, v218
	v_mul_f32_e32 v49, v49, v219
	v_mul_f32_e32 v38, v38, v220
	v_mul_f32_e32 v39, v39, v221
	v_mul_f32_e32 v40, v40, v222
	v_mul_f32_e32 v41, v41, v223
	v_mul_f32_e32 v46, v46, v42
	v_mul_f32_e32 v47, v47, v43
	v_mul_f32_e32 v48, v48, v44
	v_mul_f32_e32 v49, v49, v45
	v_mul_f32_e32 v38, v38, v34
	v_mul_f32_e32 v39, v39, v35
	v_mul_f32_e32 v40, v40, v36
	v_mul_f32_e32 v41, v41, v37
	v_cvt_pk_bf16_f32 v46, v46, v47
	v_cvt_pk_bf16_f32 v47, v48, v49
	v_cvt_pk_bf16_f32 v38, v38, v39
	v_cvt_pk_bf16_f32 v39, v40, v41
	ds_write_b64 v228, v[46:47] offset:30464
	ds_write_b64 v228, v[38:39] offset:30496
	s_waitcnt lgkmcnt(0)
	s_barrier
; __device__ __forceinline__ void phase_ffn_up(const Params& p, const u16* Wgu, u16* smem, volatile LAS unsigned* vb_) {
;     ...
; #pragma unroll
;     for (int k = 0; k < 8; ++k) {
;       const int c = tid + 512 * k;
;       const int row = c >> 4, ch = c & 15;
;       const uint4 v = *(const uint4*)(smem + row * 136 + ch * 8);
;       *(uint4*)(act + (size_t)(mt * 256 + row) * DFF + nt * 128 + ch * 8) = v;
;     }
;     __syncthreads();
	s_lshl_b32 s12, s40, 7
	s_ashr_i32 s13, s12, 31
	v_lshl_add_u64 v[38:39], s[12:13], 1, v[166:167]
	s_and_b64 vcc, exec, s[10:11]
	s_mov_b32 s20, s41
	ds_read_b128 v[34:37], v197
	s_add_i32 s49, s39, 0
	v_add_u32_e32 v40, s49, v189
	v_mad_i64_i32 v[40:41], s[12:13], v40, s7, v[38:39]
	s_waitcnt lgkmcnt(0)
	global_store_dwordx4 v[40:41], v[34:37], off
	ds_read_b128 v[34:37], v197 offset:8704
	s_add_i32 s49, s39, 32
	v_add_u32_e32 v40, s49, v189
	v_mad_i64_i32 v[40:41], s[12:13], v40, s7, v[38:39]
	s_waitcnt lgkmcnt(0)
	global_store_dwordx4 v[40:41], v[34:37], off
	ds_read_b128 v[34:37], v197 offset:17408
	s_add_i32 s49, s39, 64
	v_add_u32_e32 v40, s49, v189
	v_mad_i64_i32 v[40:41], s[12:13], v40, s7, v[38:39]
	s_waitcnt lgkmcnt(0)
	global_store_dwordx4 v[40:41], v[34:37], off
	ds_read_b128 v[34:37], v197 offset:26112
	s_add_i32 s49, s39, 96
	v_add_u32_e32 v40, s49, v189
	v_mad_i64_i32 v[40:41], s[12:13], v40, s7, v[38:39]
	s_waitcnt lgkmcnt(0)
	global_store_dwordx4 v[40:41], v[34:37], off
	ds_read_b128 v[34:37], v197 offset:34816
	s_add_i32 s49, s39, 128
	v_add_u32_e32 v40, s49, v189
	v_mad_i64_i32 v[40:41], s[12:13], v40, s7, v[38:39]
	s_waitcnt lgkmcnt(0)
	global_store_dwordx4 v[40:41], v[34:37], off
	ds_read_b128 v[34:37], v197 offset:43520
	s_add_i32 s49, s39, 160
	v_add_u32_e32 v40, s49, v189
	v_mad_i64_i32 v[40:41], s[12:13], v40, s7, v[38:39]
	s_waitcnt lgkmcnt(0)
	global_store_dwordx4 v[40:41], v[34:37], off
	ds_read_b128 v[34:37], v197 offset:52224
	s_add_i32 s49, s39, 192
	v_add_u32_e32 v40, s49, v189
	v_mad_i64_i32 v[40:41], s[12:13], v40, s7, v[38:39]
	s_waitcnt lgkmcnt(0)
	global_store_dwordx4 v[40:41], v[34:37], off
	ds_read_b128 v[34:37], v197 offset:60928
	s_add_i32 s49, s39, 224
	v_add_u32_e32 v40, s49, v189
	v_mad_i64_i32 v[40:41], s[12:13], v40, s7, v[38:39]
	s_waitcnt lgkmcnt(0)
	global_store_dwordx4 v[40:41], v[34:37], off
	s_mov_b64 s[12:13], -1
	s_barrier
	s_cbranch_vccz .LBB0_598
